# pool-fold weight loops (both copies) rewritten: 32 row loads in flight rolling window instead of 8 / serialized 1, a=pw*ps via per-lane product + v_readlane
# speedup vs baseline: 1.0157x; 1.0063x over previous
; #define BIDX opaque_bid()
; DEVI void convert_layer(const Params& p, int layer, char* smem) {
;     ...
;       for (int item = BIDX; item < 512; item += gridDim.x) {
;         const int g = item >> 7, c = item & 127;
;         const float* pwr = pw + ((size_t)g * 128 + c) * 128;
;         const float* wor = wo + (size_t)(512 + g * 128) * 1024 + tid * 4;
;         f32x4 acc = f32x4{0.f, 0.f, 0.f, 0.f};
; #pragma unroll 8
;         for (int d = 0; d < 128; ++d) {
;           const float a = pwr[d] * ps[g * 128 + d];
;           const f32x4 w4 = *(const f32x4*)(wor + (size_t)d * 1024);
;           acc = acc + w4 * a;
;         }
.LBB0_1680:
	v_and_b32_e32 v0, 63, v206
	v_lshlrev_b32_e32 v0, 2, v0
	s_mov_b32 s38, s35
	s_mov_b32 s39, s36
	global_load_dword v142, v0, s[38:39]
	global_load_dword v143, v0, s[38:39] offset:256
	s_mov_b32 s38, s25
	s_mov_b32 s39, s34
	global_load_dword v144, v0, s[38:39]
	global_load_dword v145, v0, s[38:39] offset:256
	s_mov_b32 s16, 0xffffa000
	s_mov_b32 s17, -1
	v_lshl_add_u64 v[6:7], v[6:7], 0, s[16:17]
	s_mov_b64 vcc, 0x2000
	global_load_dwordx4 v[14:17], v[6:7], off offset:-4096
	global_load_dwordx4 v[18:21], v[6:7], off
	v_lshl_add_u64 v[6:7], v[6:7], 0, vcc
	global_load_dwordx4 v[22:25], v[6:7], off offset:-4096
	global_load_dwordx4 v[26:29], v[6:7], off
	v_lshl_add_u64 v[6:7], v[6:7], 0, vcc
	global_load_dwordx4 v[30:33], v[6:7], off offset:-4096
	global_load_dwordx4 v[34:37], v[6:7], off
	v_lshl_add_u64 v[6:7], v[6:7], 0, vcc
	global_load_dwordx4 v[38:41], v[6:7], off offset:-4096
	global_load_dwordx4 v[42:45], v[6:7], off
	v_lshl_add_u64 v[6:7], v[6:7], 0, vcc
	global_load_dwordx4 v[46:49], v[6:7], off offset:-4096
	global_load_dwordx4 v[50:53], v[6:7], off
	v_lshl_add_u64 v[6:7], v[6:7], 0, vcc
	global_load_dwordx4 v[54:57], v[6:7], off offset:-4096
	global_load_dwordx4 v[58:61], v[6:7], off
	v_lshl_add_u64 v[6:7], v[6:7], 0, vcc
	global_load_dwordx4 v[62:65], v[6:7], off offset:-4096
	global_load_dwordx4 v[66:69], v[6:7], off
	v_lshl_add_u64 v[6:7], v[6:7], 0, vcc
	global_load_dwordx4 v[70:73], v[6:7], off offset:-4096
	global_load_dwordx4 v[74:77], v[6:7], off
	v_lshl_add_u64 v[6:7], v[6:7], 0, vcc
	global_load_dwordx4 v[78:81], v[6:7], off offset:-4096
	global_load_dwordx4 v[82:85], v[6:7], off
	v_lshl_add_u64 v[6:7], v[6:7], 0, vcc
	global_load_dwordx4 v[86:89], v[6:7], off offset:-4096
	global_load_dwordx4 v[90:93], v[6:7], off
	v_lshl_add_u64 v[6:7], v[6:7], 0, vcc
	global_load_dwordx4 v[94:97], v[6:7], off offset:-4096
	global_load_dwordx4 v[98:101], v[6:7], off
	v_lshl_add_u64 v[6:7], v[6:7], 0, vcc
	global_load_dwordx4 v[102:105], v[6:7], off offset:-4096
	global_load_dwordx4 v[106:109], v[6:7], off
	v_lshl_add_u64 v[6:7], v[6:7], 0, vcc
	global_load_dwordx4 v[110:113], v[6:7], off offset:-4096
	global_load_dwordx4 v[114:117], v[6:7], off
	v_lshl_add_u64 v[6:7], v[6:7], 0, vcc
	global_load_dwordx4 v[118:121], v[6:7], off offset:-4096
	global_load_dwordx4 v[122:125], v[6:7], off
	v_lshl_add_u64 v[6:7], v[6:7], 0, vcc
	global_load_dwordx4 v[126:129], v[6:7], off offset:-4096
	global_load_dwordx4 v[130:133], v[6:7], off
	v_lshl_add_u64 v[6:7], v[6:7], 0, vcc
	global_load_dwordx4 v[134:137], v[6:7], off offset:-4096
	global_load_dwordx4 v[138:141], v[6:7], off
	v_lshl_add_u64 v[6:7], v[6:7], 0, vcc
	s_waitcnt vmcnt(32)
	v_mul_f32_e32 v142, v142, v144
	v_mul_f32_e32 v143, v143, v145
	s_nop 1
	v_readlane_b32 s16, v142, 0
	v_readlane_b32 s17, v142, 1
	v_readlane_b32 s38, v142, 2
	v_readlane_b32 s39, v142, 3
	s_waitcnt vmcnt(31)
	v_fmac_f32_e32 v10, s16, v14
	v_fmac_f32_e32 v11, s16, v15
	v_fmac_f32_e32 v8, s16, v16
	v_fmac_f32_e32 v9, s16, v17
	global_load_dwordx4 v[14:17], v[6:7], off offset:-4096
	s_waitcnt vmcnt(31)
	v_fmac_f32_e32 v10, s17, v18
	v_fmac_f32_e32 v11, s17, v19
	v_fmac_f32_e32 v8, s17, v20
	v_fmac_f32_e32 v9, s17, v21
	global_load_dwordx4 v[18:21], v[6:7], off
	v_lshl_add_u64 v[6:7], v[6:7], 0, vcc
	s_waitcnt vmcnt(31)
	v_fmac_f32_e32 v10, s38, v22
	v_fmac_f32_e32 v11, s38, v23
	v_fmac_f32_e32 v8, s38, v24
	v_fmac_f32_e32 v9, s38, v25
	global_load_dwordx4 v[22:25], v[6:7], off offset:-4096
	s_waitcnt vmcnt(31)
	v_fmac_f32_e32 v10, s39, v26
	v_fmac_f32_e32 v11, s39, v27
	v_fmac_f32_e32 v8, s39, v28
	v_fmac_f32_e32 v9, s39, v29
	global_load_dwordx4 v[26:29], v[6:7], off
	v_lshl_add_u64 v[6:7], v[6:7], 0, vcc
	v_readlane_b32 s16, v142, 4
	v_readlane_b32 s17, v142, 5
	v_readlane_b32 s38, v142, 6
	v_readlane_b32 s39, v142, 7
	s_waitcnt vmcnt(31)
	v_fmac_f32_e32 v10, s16, v30
	v_fmac_f32_e32 v11, s16, v31
	v_fmac_f32_e32 v8, s16, v32
	v_fmac_f32_e32 v9, s16, v33
	global_load_dwordx4 v[30:33], v[6:7], off offset:-4096
	s_waitcnt vmcnt(31)
	v_fmac_f32_e32 v10, s17, v34
	v_fmac_f32_e32 v11, s17, v35
	v_fmac_f32_e32 v8, s17, v36
	v_fmac_f32_e32 v9, s17, v37
	global_load_dwordx4 v[34:37], v[6:7], off
	v_lshl_add_u64 v[6:7], v[6:7], 0, vcc
	s_waitcnt vmcnt(31)
	v_fmac_f32_e32 v10, s38, v38
	v_fmac_f32_e32 v11, s38, v39
	v_fmac_f32_e32 v8, s38, v40
	v_fmac_f32_e32 v9, s38, v41
	global_load_dwordx4 v[38:41], v[6:7], off offset:-4096
	s_waitcnt vmcnt(31)
	v_fmac_f32_e32 v10, s39, v42
	v_fmac_f32_e32 v11, s39, v43
	v_fmac_f32_e32 v8, s39, v44
	v_fmac_f32_e32 v9, s39, v45
	global_load_dwordx4 v[42:45], v[6:7], off
	v_lshl_add_u64 v[6:7], v[6:7], 0, vcc
	v_readlane_b32 s16, v142, 8
	v_readlane_b32 s17, v142, 9
	v_readlane_b32 s38, v142, 10
	v_readlane_b32 s39, v142, 11
	s_waitcnt vmcnt(31)
	v_fmac_f32_e32 v10, s16, v46
	v_fmac_f32_e32 v11, s16, v47
	v_fmac_f32_e32 v8, s16, v48
	v_fmac_f32_e32 v9, s16, v49
	global_load_dwordx4 v[46:49], v[6:7], off offset:-4096
	s_waitcnt vmcnt(31)
	v_fmac_f32_e32 v10, s17, v50
	v_fmac_f32_e32 v11, s17, v51
	v_fmac_f32_e32 v8, s17, v52
	v_fmac_f32_e32 v9, s17, v53
	global_load_dwordx4 v[50:53], v[6:7], off
	v_lshl_add_u64 v[6:7], v[6:7], 0, vcc
	s_waitcnt vmcnt(31)
	v_fmac_f32_e32 v10, s38, v54
	v_fmac_f32_e32 v11, s38, v55
	v_fmac_f32_e32 v8, s38, v56
	v_fmac_f32_e32 v9, s38, v57
	global_load_dwordx4 v[54:57], v[6:7], off offset:-4096
	s_waitcnt vmcnt(31)
	v_fmac_f32_e32 v10, s39, v58
	v_fmac_f32_e32 v11, s39, v59
	v_fmac_f32_e32 v8, s39, v60
	v_fmac_f32_e32 v9, s39, v61
	global_load_dwordx4 v[58:61], v[6:7], off
	v_lshl_add_u64 v[6:7], v[6:7], 0, vcc
	v_readlane_b32 s16, v142, 12
	v_readlane_b32 s17, v142, 13
	v_readlane_b32 s38, v142, 14
	v_readlane_b32 s39, v142, 15
	s_waitcnt vmcnt(31)
; DEVI void convert_layer(const Params& p, int layer, char* smem) {
;     ...
;         for (int d = 0; d < 128; ++d) {
;           const float a = pwr[d] * ps[g * 128 + d];
;           const f32x4 w4 = *(const f32x4*)(wor + (size_t)d * 1024);
;           acc = acc + w4 * a;
;         }
	v_fmac_f32_e32 v10, s16, v62
	v_fmac_f32_e32 v11, s16, v63
	v_fmac_f32_e32 v8, s16, v64
	v_fmac_f32_e32 v9, s16, v65
	global_load_dwordx4 v[62:65], v[6:7], off offset:-4096
	s_waitcnt vmcnt(31)
	v_fmac_f32_e32 v10, s17, v66
	v_fmac_f32_e32 v11, s17, v67
	v_fmac_f32_e32 v8, s17, v68
	v_fmac_f32_e32 v9, s17, v69
	global_load_dwordx4 v[66:69], v[6:7], off
	v_lshl_add_u64 v[6:7], v[6:7], 0, vcc
	s_waitcnt vmcnt(31)
	v_fmac_f32_e32 v10, s38, v70
	v_fmac_f32_e32 v11, s38, v71
	v_fmac_f32_e32 v8, s38, v72
	v_fmac_f32_e32 v9, s38, v73
	global_load_dwordx4 v[70:73], v[6:7], off offset:-4096
	s_waitcnt vmcnt(31)
	v_fmac_f32_e32 v10, s39, v74
	v_fmac_f32_e32 v11, s39, v75
	v_fmac_f32_e32 v8, s39, v76
	v_fmac_f32_e32 v9, s39, v77
	global_load_dwordx4 v[74:77], v[6:7], off
	v_lshl_add_u64 v[6:7], v[6:7], 0, vcc
	v_readlane_b32 s16, v142, 16
	v_readlane_b32 s17, v142, 17
	v_readlane_b32 s38, v142, 18
	v_readlane_b32 s39, v142, 19
	s_waitcnt vmcnt(31)
	v_fmac_f32_e32 v10, s16, v78
	v_fmac_f32_e32 v11, s16, v79
	v_fmac_f32_e32 v8, s16, v80
	v_fmac_f32_e32 v9, s16, v81
	global_load_dwordx4 v[78:81], v[6:7], off offset:-4096
	s_waitcnt vmcnt(31)
	v_fmac_f32_e32 v10, s17, v82
	v_fmac_f32_e32 v11, s17, v83
	v_fmac_f32_e32 v8, s17, v84
	v_fmac_f32_e32 v9, s17, v85
	global_load_dwordx4 v[82:85], v[6:7], off
	v_lshl_add_u64 v[6:7], v[6:7], 0, vcc
	s_waitcnt vmcnt(31)
	v_fmac_f32_e32 v10, s38, v86
	v_fmac_f32_e32 v11, s38, v87
	v_fmac_f32_e32 v8, s38, v88
	v_fmac_f32_e32 v9, s38, v89
	global_load_dwordx4 v[86:89], v[6:7], off offset:-4096
	s_waitcnt vmcnt(31)
	v_fmac_f32_e32 v10, s39, v90
	v_fmac_f32_e32 v11, s39, v91
	v_fmac_f32_e32 v8, s39, v92
	v_fmac_f32_e32 v9, s39, v93
	global_load_dwordx4 v[90:93], v[6:7], off
	v_lshl_add_u64 v[6:7], v[6:7], 0, vcc
	v_readlane_b32 s16, v142, 20
	v_readlane_b32 s17, v142, 21
	v_readlane_b32 s38, v142, 22
	v_readlane_b32 s39, v142, 23
	s_waitcnt vmcnt(31)
	v_fmac_f32_e32 v10, s16, v94
	v_fmac_f32_e32 v11, s16, v95
	v_fmac_f32_e32 v8, s16, v96
	v_fmac_f32_e32 v9, s16, v97
	global_load_dwordx4 v[94:97], v[6:7], off offset:-4096
	s_waitcnt vmcnt(31)
	v_fmac_f32_e32 v10, s17, v98
	v_fmac_f32_e32 v11, s17, v99
	v_fmac_f32_e32 v8, s17, v100
	v_fmac_f32_e32 v9, s17, v101
	global_load_dwordx4 v[98:101], v[6:7], off
	v_lshl_add_u64 v[6:7], v[6:7], 0, vcc
	s_waitcnt vmcnt(31)
	v_fmac_f32_e32 v10, s38, v102
	v_fmac_f32_e32 v11, s38, v103
	v_fmac_f32_e32 v8, s38, v104
	v_fmac_f32_e32 v9, s38, v105
	global_load_dwordx4 v[102:105], v[6:7], off offset:-4096
	s_waitcnt vmcnt(31)
	v_fmac_f32_e32 v10, s39, v106
	v_fmac_f32_e32 v11, s39, v107
	v_fmac_f32_e32 v8, s39, v108
	v_fmac_f32_e32 v9, s39, v109
	global_load_dwordx4 v[106:109], v[6:7], off
	v_lshl_add_u64 v[6:7], v[6:7], 0, vcc
	v_readlane_b32 s16, v142, 24
	v_readlane_b32 s17, v142, 25
	v_readlane_b32 s38, v142, 26
	v_readlane_b32 s39, v142, 27
	s_waitcnt vmcnt(31)
	v_fmac_f32_e32 v10, s16, v110
	v_fmac_f32_e32 v11, s16, v111
	v_fmac_f32_e32 v8, s16, v112
	v_fmac_f32_e32 v9, s16, v113
	global_load_dwordx4 v[110:113], v[6:7], off offset:-4096
	s_waitcnt vmcnt(31)
	v_fmac_f32_e32 v10, s17, v114
	v_fmac_f32_e32 v11, s17, v115
	v_fmac_f32_e32 v8, s17, v116
	v_fmac_f32_e32 v9, s17, v117
	global_load_dwordx4 v[114:117], v[6:7], off
	v_lshl_add_u64 v[6:7], v[6:7], 0, vcc
	s_waitcnt vmcnt(31)
	v_fmac_f32_e32 v10, s38, v118
	v_fmac_f32_e32 v11, s38, v119
	v_fmac_f32_e32 v8, s38, v120
	v_fmac_f32_e32 v9, s38, v121
	global_load_dwordx4 v[118:121], v[6:7], off offset:-4096
	s_waitcnt vmcnt(31)
	v_fmac_f32_e32 v10, s39, v122
	v_fmac_f32_e32 v11, s39, v123
	v_fmac_f32_e32 v8, s39, v124
	v_fmac_f32_e32 v9, s39, v125
	global_load_dwordx4 v[122:125], v[6:7], off
	v_lshl_add_u64 v[6:7], v[6:7], 0, vcc
	v_readlane_b32 s16, v142, 28
	v_readlane_b32 s17, v142, 29
	v_readlane_b32 s38, v142, 30
	v_readlane_b32 s39, v142, 31
	s_waitcnt vmcnt(31)
	v_fmac_f32_e32 v10, s16, v126
	v_fmac_f32_e32 v11, s16, v127
	v_fmac_f32_e32 v8, s16, v128
	v_fmac_f32_e32 v9, s16, v129
	global_load_dwordx4 v[126:129], v[6:7], off offset:-4096
	s_waitcnt vmcnt(31)
	v_fmac_f32_e32 v10, s17, v130
	v_fmac_f32_e32 v11, s17, v131
	v_fmac_f32_e32 v8, s17, v132
	v_fmac_f32_e32 v9, s17, v133
	global_load_dwordx4 v[130:133], v[6:7], off
	v_lshl_add_u64 v[6:7], v[6:7], 0, vcc
	s_waitcnt vmcnt(31)
	v_fmac_f32_e32 v10, s38, v134
	v_fmac_f32_e32 v11, s38, v135
	v_fmac_f32_e32 v8, s38, v136
	v_fmac_f32_e32 v9, s38, v137
	global_load_dwordx4 v[134:137], v[6:7], off offset:-4096
	s_waitcnt vmcnt(31)
	v_fmac_f32_e32 v10, s39, v138
	v_fmac_f32_e32 v11, s39, v139
	v_fmac_f32_e32 v8, s39, v140
	v_fmac_f32_e32 v9, s39, v141
	global_load_dwordx4 v[138:141], v[6:7], off
	v_lshl_add_u64 v[6:7], v[6:7], 0, vcc
	v_readlane_b32 s16, v142, 32
	v_readlane_b32 s17, v142, 33
	v_readlane_b32 s38, v142, 34
	v_readlane_b32 s39, v142, 35
	s_waitcnt vmcnt(31)
	v_fmac_f32_e32 v10, s16, v14
	v_fmac_f32_e32 v11, s16, v15
	v_fmac_f32_e32 v8, s16, v16
	v_fmac_f32_e32 v9, s16, v17
	global_load_dwordx4 v[14:17], v[6:7], off offset:-4096
	s_waitcnt vmcnt(31)
	v_fmac_f32_e32 v10, s17, v18
	v_fmac_f32_e32 v11, s17, v19
	v_fmac_f32_e32 v8, s17, v20
	v_fmac_f32_e32 v9, s17, v21
	global_load_dwordx4 v[18:21], v[6:7], off
	v_lshl_add_u64 v[6:7], v[6:7], 0, vcc
	s_waitcnt vmcnt(31)
	v_fmac_f32_e32 v10, s38, v22
	v_fmac_f32_e32 v11, s38, v23
	v_fmac_f32_e32 v8, s38, v24
	v_fmac_f32_e32 v9, s38, v25
	global_load_dwordx4 v[22:25], v[6:7], off offset:-4096
	s_waitcnt vmcnt(31)
	v_fmac_f32_e32 v10, s39, v26
	v_fmac_f32_e32 v11, s39, v27
	v_fmac_f32_e32 v8, s39, v28
	v_fmac_f32_e32 v9, s39, v29
	global_load_dwordx4 v[26:29], v[6:7], off
	v_lshl_add_u64 v[6:7], v[6:7], 0, vcc
	v_readlane_b32 s16, v142, 36
	v_readlane_b32 s17, v142, 37
	v_readlane_b32 s38, v142, 38
	v_readlane_b32 s39, v142, 39
	s_waitcnt vmcnt(31)
; DEVI void convert_layer(const Params& p, int layer, char* smem) {
;     ...
;         for (int d = 0; d < 128; ++d) {
;           const float a = pwr[d] * ps[g * 128 + d];
;           const f32x4 w4 = *(const f32x4*)(wor + (size_t)d * 1024);
;           acc = acc + w4 * a;
;         }
	v_fmac_f32_e32 v10, s16, v30
	v_fmac_f32_e32 v11, s16, v31
	v_fmac_f32_e32 v8, s16, v32
	v_fmac_f32_e32 v9, s16, v33
	global_load_dwordx4 v[30:33], v[6:7], off offset:-4096
	s_waitcnt vmcnt(31)
	v_fmac_f32_e32 v10, s17, v34
	v_fmac_f32_e32 v11, s17, v35
	v_fmac_f32_e32 v8, s17, v36
	v_fmac_f32_e32 v9, s17, v37
	global_load_dwordx4 v[34:37], v[6:7], off
	v_lshl_add_u64 v[6:7], v[6:7], 0, vcc
	s_waitcnt vmcnt(31)
	v_fmac_f32_e32 v10, s38, v38
	v_fmac_f32_e32 v11, s38, v39
	v_fmac_f32_e32 v8, s38, v40
	v_fmac_f32_e32 v9, s38, v41
	global_load_dwordx4 v[38:41], v[6:7], off offset:-4096
	s_waitcnt vmcnt(31)
	v_fmac_f32_e32 v10, s39, v42
	v_fmac_f32_e32 v11, s39, v43
	v_fmac_f32_e32 v8, s39, v44
	v_fmac_f32_e32 v9, s39, v45
	global_load_dwordx4 v[42:45], v[6:7], off
	v_lshl_add_u64 v[6:7], v[6:7], 0, vcc
	v_readlane_b32 s16, v142, 40
	v_readlane_b32 s17, v142, 41
	v_readlane_b32 s38, v142, 42
	v_readlane_b32 s39, v142, 43
	s_waitcnt vmcnt(31)
	v_fmac_f32_e32 v10, s16, v46
	v_fmac_f32_e32 v11, s16, v47
	v_fmac_f32_e32 v8, s16, v48
	v_fmac_f32_e32 v9, s16, v49
	global_load_dwordx4 v[46:49], v[6:7], off offset:-4096
	s_waitcnt vmcnt(31)
	v_fmac_f32_e32 v10, s17, v50
	v_fmac_f32_e32 v11, s17, v51
	v_fmac_f32_e32 v8, s17, v52
	v_fmac_f32_e32 v9, s17, v53
	global_load_dwordx4 v[50:53], v[6:7], off
	v_lshl_add_u64 v[6:7], v[6:7], 0, vcc
	s_waitcnt vmcnt(31)
	v_fmac_f32_e32 v10, s38, v54
	v_fmac_f32_e32 v11, s38, v55
	v_fmac_f32_e32 v8, s38, v56
	v_fmac_f32_e32 v9, s38, v57
	global_load_dwordx4 v[54:57], v[6:7], off offset:-4096
	s_waitcnt vmcnt(31)
	v_fmac_f32_e32 v10, s39, v58
	v_fmac_f32_e32 v11, s39, v59
	v_fmac_f32_e32 v8, s39, v60
	v_fmac_f32_e32 v9, s39, v61
	global_load_dwordx4 v[58:61], v[6:7], off
	v_lshl_add_u64 v[6:7], v[6:7], 0, vcc
	v_readlane_b32 s16, v142, 44
	v_readlane_b32 s17, v142, 45
	v_readlane_b32 s38, v142, 46
	v_readlane_b32 s39, v142, 47
	s_waitcnt vmcnt(31)
	v_fmac_f32_e32 v10, s16, v62
	v_fmac_f32_e32 v11, s16, v63
	v_fmac_f32_e32 v8, s16, v64
	v_fmac_f32_e32 v9, s16, v65
	global_load_dwordx4 v[62:65], v[6:7], off offset:-4096
	s_waitcnt vmcnt(31)
	v_fmac_f32_e32 v10, s17, v66
	v_fmac_f32_e32 v11, s17, v67
	v_fmac_f32_e32 v8, s17, v68
	v_fmac_f32_e32 v9, s17, v69
	global_load_dwordx4 v[66:69], v[6:7], off
	v_lshl_add_u64 v[6:7], v[6:7], 0, vcc
	s_waitcnt vmcnt(31)
	v_fmac_f32_e32 v10, s38, v70
	v_fmac_f32_e32 v11, s38, v71
	v_fmac_f32_e32 v8, s38, v72
	v_fmac_f32_e32 v9, s38, v73
	global_load_dwordx4 v[70:73], v[6:7], off offset:-4096
	s_waitcnt vmcnt(31)
	v_fmac_f32_e32 v10, s39, v74
	v_fmac_f32_e32 v11, s39, v75
	v_fmac_f32_e32 v8, s39, v76
	v_fmac_f32_e32 v9, s39, v77
	global_load_dwordx4 v[74:77], v[6:7], off
	v_lshl_add_u64 v[6:7], v[6:7], 0, vcc
	v_readlane_b32 s16, v142, 48
	v_readlane_b32 s17, v142, 49
	v_readlane_b32 s38, v142, 50
	v_readlane_b32 s39, v142, 51
	s_waitcnt vmcnt(31)
	v_fmac_f32_e32 v10, s16, v78
	v_fmac_f32_e32 v11, s16, v79
	v_fmac_f32_e32 v8, s16, v80
	v_fmac_f32_e32 v9, s16, v81
	global_load_dwordx4 v[78:81], v[6:7], off offset:-4096
	s_waitcnt vmcnt(31)
	v_fmac_f32_e32 v10, s17, v82
	v_fmac_f32_e32 v11, s17, v83
	v_fmac_f32_e32 v8, s17, v84
	v_fmac_f32_e32 v9, s17, v85
	global_load_dwordx4 v[82:85], v[6:7], off
	v_lshl_add_u64 v[6:7], v[6:7], 0, vcc
	s_waitcnt vmcnt(31)
	v_fmac_f32_e32 v10, s38, v86
	v_fmac_f32_e32 v11, s38, v87
	v_fmac_f32_e32 v8, s38, v88
	v_fmac_f32_e32 v9, s38, v89
	global_load_dwordx4 v[86:89], v[6:7], off offset:-4096
	s_waitcnt vmcnt(31)
	v_fmac_f32_e32 v10, s39, v90
	v_fmac_f32_e32 v11, s39, v91
	v_fmac_f32_e32 v8, s39, v92
	v_fmac_f32_e32 v9, s39, v93
	global_load_dwordx4 v[90:93], v[6:7], off
	v_lshl_add_u64 v[6:7], v[6:7], 0, vcc
	v_readlane_b32 s16, v142, 52
	v_readlane_b32 s17, v142, 53
	v_readlane_b32 s38, v142, 54
	v_readlane_b32 s39, v142, 55
	s_waitcnt vmcnt(31)
	v_fmac_f32_e32 v10, s16, v94
	v_fmac_f32_e32 v11, s16, v95
	v_fmac_f32_e32 v8, s16, v96
	v_fmac_f32_e32 v9, s16, v97
	global_load_dwordx4 v[94:97], v[6:7], off offset:-4096
	s_waitcnt vmcnt(31)
	v_fmac_f32_e32 v10, s17, v98
	v_fmac_f32_e32 v11, s17, v99
	v_fmac_f32_e32 v8, s17, v100
	v_fmac_f32_e32 v9, s17, v101
	global_load_dwordx4 v[98:101], v[6:7], off
	v_lshl_add_u64 v[6:7], v[6:7], 0, vcc
	s_waitcnt vmcnt(31)
	v_fmac_f32_e32 v10, s38, v102
	v_fmac_f32_e32 v11, s38, v103
	v_fmac_f32_e32 v8, s38, v104
	v_fmac_f32_e32 v9, s38, v105
	global_load_dwordx4 v[102:105], v[6:7], off offset:-4096
	s_waitcnt vmcnt(31)
	v_fmac_f32_e32 v10, s39, v106
	v_fmac_f32_e32 v11, s39, v107
	v_fmac_f32_e32 v8, s39, v108
	v_fmac_f32_e32 v9, s39, v109
	global_load_dwordx4 v[106:109], v[6:7], off
	v_lshl_add_u64 v[6:7], v[6:7], 0, vcc
	v_readlane_b32 s16, v142, 56
	v_readlane_b32 s17, v142, 57
	v_readlane_b32 s38, v142, 58
	v_readlane_b32 s39, v142, 59
	s_waitcnt vmcnt(31)
	v_fmac_f32_e32 v10, s16, v110
	v_fmac_f32_e32 v11, s16, v111
	v_fmac_f32_e32 v8, s16, v112
	v_fmac_f32_e32 v9, s16, v113
	global_load_dwordx4 v[110:113], v[6:7], off offset:-4096
	s_waitcnt vmcnt(31)
	v_fmac_f32_e32 v10, s17, v114
	v_fmac_f32_e32 v11, s17, v115
	v_fmac_f32_e32 v8, s17, v116
	v_fmac_f32_e32 v9, s17, v117
	global_load_dwordx4 v[114:117], v[6:7], off
	v_lshl_add_u64 v[6:7], v[6:7], 0, vcc
	s_waitcnt vmcnt(31)
	v_fmac_f32_e32 v10, s38, v118
	v_fmac_f32_e32 v11, s38, v119
	v_fmac_f32_e32 v8, s38, v120
	v_fmac_f32_e32 v9, s38, v121
	global_load_dwordx4 v[118:121], v[6:7], off offset:-4096
	s_waitcnt vmcnt(31)
	v_fmac_f32_e32 v10, s39, v122
	v_fmac_f32_e32 v11, s39, v123
	v_fmac_f32_e32 v8, s39, v124
	v_fmac_f32_e32 v9, s39, v125
	global_load_dwordx4 v[122:125], v[6:7], off
	v_lshl_add_u64 v[6:7], v[6:7], 0, vcc
	v_readlane_b32 s16, v142, 60
	v_readlane_b32 s17, v142, 61
	v_readlane_b32 s38, v142, 62
	v_readlane_b32 s39, v142, 63
	s_waitcnt vmcnt(31)
; DEVI void convert_layer(const Params& p, int layer, char* smem) {
;     ...
;         for (int d = 0; d < 128; ++d) {
;           const float a = pwr[d] * ps[g * 128 + d];
;           const f32x4 w4 = *(const f32x4*)(wor + (size_t)d * 1024);
;           acc = acc + w4 * a;
;         }
	v_fmac_f32_e32 v10, s16, v126
	v_fmac_f32_e32 v11, s16, v127
	v_fmac_f32_e32 v8, s16, v128
	v_fmac_f32_e32 v9, s16, v129
	global_load_dwordx4 v[126:129], v[6:7], off offset:-4096
	s_waitcnt vmcnt(31)
	v_fmac_f32_e32 v10, s17, v130
	v_fmac_f32_e32 v11, s17, v131
	v_fmac_f32_e32 v8, s17, v132
	v_fmac_f32_e32 v9, s17, v133
	global_load_dwordx4 v[130:133], v[6:7], off
	v_lshl_add_u64 v[6:7], v[6:7], 0, vcc
	s_waitcnt vmcnt(31)
	v_fmac_f32_e32 v10, s38, v134
	v_fmac_f32_e32 v11, s38, v135
	v_fmac_f32_e32 v8, s38, v136
	v_fmac_f32_e32 v9, s38, v137
	global_load_dwordx4 v[134:137], v[6:7], off offset:-4096
	s_waitcnt vmcnt(31)
	v_fmac_f32_e32 v10, s39, v138
	v_fmac_f32_e32 v11, s39, v139
	v_fmac_f32_e32 v8, s39, v140
	v_fmac_f32_e32 v9, s39, v141
	global_load_dwordx4 v[138:141], v[6:7], off
	v_lshl_add_u64 v[6:7], v[6:7], 0, vcc
	v_readlane_b32 s16, v143, 0
	v_readlane_b32 s17, v143, 1
	v_readlane_b32 s38, v143, 2
	v_readlane_b32 s39, v143, 3
	s_waitcnt vmcnt(31)
	v_fmac_f32_e32 v10, s16, v14
	v_fmac_f32_e32 v11, s16, v15
	v_fmac_f32_e32 v8, s16, v16
	v_fmac_f32_e32 v9, s16, v17
	global_load_dwordx4 v[14:17], v[6:7], off offset:-4096
	s_waitcnt vmcnt(31)
	v_fmac_f32_e32 v10, s17, v18
	v_fmac_f32_e32 v11, s17, v19
	v_fmac_f32_e32 v8, s17, v20
	v_fmac_f32_e32 v9, s17, v21
	global_load_dwordx4 v[18:21], v[6:7], off
	v_lshl_add_u64 v[6:7], v[6:7], 0, vcc
	s_waitcnt vmcnt(31)
	v_fmac_f32_e32 v10, s38, v22
	v_fmac_f32_e32 v11, s38, v23
	v_fmac_f32_e32 v8, s38, v24
	v_fmac_f32_e32 v9, s38, v25
	global_load_dwordx4 v[22:25], v[6:7], off offset:-4096
	s_waitcnt vmcnt(31)
	v_fmac_f32_e32 v10, s39, v26
	v_fmac_f32_e32 v11, s39, v27
	v_fmac_f32_e32 v8, s39, v28
	v_fmac_f32_e32 v9, s39, v29
	global_load_dwordx4 v[26:29], v[6:7], off
	v_lshl_add_u64 v[6:7], v[6:7], 0, vcc
	v_readlane_b32 s16, v143, 4
	v_readlane_b32 s17, v143, 5
	v_readlane_b32 s38, v143, 6
	v_readlane_b32 s39, v143, 7
	s_waitcnt vmcnt(31)
	v_fmac_f32_e32 v10, s16, v30
	v_fmac_f32_e32 v11, s16, v31
	v_fmac_f32_e32 v8, s16, v32
	v_fmac_f32_e32 v9, s16, v33
	global_load_dwordx4 v[30:33], v[6:7], off offset:-4096
	s_waitcnt vmcnt(31)
	v_fmac_f32_e32 v10, s17, v34
	v_fmac_f32_e32 v11, s17, v35
	v_fmac_f32_e32 v8, s17, v36
	v_fmac_f32_e32 v9, s17, v37
	global_load_dwordx4 v[34:37], v[6:7], off
	v_lshl_add_u64 v[6:7], v[6:7], 0, vcc
	s_waitcnt vmcnt(31)
	v_fmac_f32_e32 v10, s38, v38
	v_fmac_f32_e32 v11, s38, v39
	v_fmac_f32_e32 v8, s38, v40
	v_fmac_f32_e32 v9, s38, v41
	global_load_dwordx4 v[38:41], v[6:7], off offset:-4096
	s_waitcnt vmcnt(31)
	v_fmac_f32_e32 v10, s39, v42
	v_fmac_f32_e32 v11, s39, v43
	v_fmac_f32_e32 v8, s39, v44
	v_fmac_f32_e32 v9, s39, v45
	global_load_dwordx4 v[42:45], v[6:7], off
	v_lshl_add_u64 v[6:7], v[6:7], 0, vcc
	v_readlane_b32 s16, v143, 8
	v_readlane_b32 s17, v143, 9
	v_readlane_b32 s38, v143, 10
	v_readlane_b32 s39, v143, 11
	s_waitcnt vmcnt(31)
	v_fmac_f32_e32 v10, s16, v46
	v_fmac_f32_e32 v11, s16, v47
	v_fmac_f32_e32 v8, s16, v48
	v_fmac_f32_e32 v9, s16, v49
	global_load_dwordx4 v[46:49], v[6:7], off offset:-4096
	s_waitcnt vmcnt(31)
	v_fmac_f32_e32 v10, s17, v50
	v_fmac_f32_e32 v11, s17, v51
	v_fmac_f32_e32 v8, s17, v52
	v_fmac_f32_e32 v9, s17, v53
	global_load_dwordx4 v[50:53], v[6:7], off
	v_lshl_add_u64 v[6:7], v[6:7], 0, vcc
	s_waitcnt vmcnt(31)
	v_fmac_f32_e32 v10, s38, v54
	v_fmac_f32_e32 v11, s38, v55
	v_fmac_f32_e32 v8, s38, v56
	v_fmac_f32_e32 v9, s38, v57
	global_load_dwordx4 v[54:57], v[6:7], off offset:-4096
	s_waitcnt vmcnt(31)
	v_fmac_f32_e32 v10, s39, v58
	v_fmac_f32_e32 v11, s39, v59
	v_fmac_f32_e32 v8, s39, v60
	v_fmac_f32_e32 v9, s39, v61
	global_load_dwordx4 v[58:61], v[6:7], off
	v_lshl_add_u64 v[6:7], v[6:7], 0, vcc
	v_readlane_b32 s16, v143, 12
	v_readlane_b32 s17, v143, 13
	v_readlane_b32 s38, v143, 14
	v_readlane_b32 s39, v143, 15
	s_waitcnt vmcnt(31)
	v_fmac_f32_e32 v10, s16, v62
	v_fmac_f32_e32 v11, s16, v63
	v_fmac_f32_e32 v8, s16, v64
	v_fmac_f32_e32 v9, s16, v65
	global_load_dwordx4 v[62:65], v[6:7], off offset:-4096
	s_waitcnt vmcnt(31)
	v_fmac_f32_e32 v10, s17, v66
	v_fmac_f32_e32 v11, s17, v67
	v_fmac_f32_e32 v8, s17, v68
	v_fmac_f32_e32 v9, s17, v69
	global_load_dwordx4 v[66:69], v[6:7], off
	v_lshl_add_u64 v[6:7], v[6:7], 0, vcc
	s_waitcnt vmcnt(31)
	v_fmac_f32_e32 v10, s38, v70
	v_fmac_f32_e32 v11, s38, v71
	v_fmac_f32_e32 v8, s38, v72
	v_fmac_f32_e32 v9, s38, v73
	global_load_dwordx4 v[70:73], v[6:7], off offset:-4096
	s_waitcnt vmcnt(31)
	v_fmac_f32_e32 v10, s39, v74
	v_fmac_f32_e32 v11, s39, v75
	v_fmac_f32_e32 v8, s39, v76
	v_fmac_f32_e32 v9, s39, v77
	global_load_dwordx4 v[74:77], v[6:7], off
	v_lshl_add_u64 v[6:7], v[6:7], 0, vcc
	v_readlane_b32 s16, v143, 16
	v_readlane_b32 s17, v143, 17
	v_readlane_b32 s38, v143, 18
	v_readlane_b32 s39, v143, 19
	s_waitcnt vmcnt(31)
	v_fmac_f32_e32 v10, s16, v78
	v_fmac_f32_e32 v11, s16, v79
	v_fmac_f32_e32 v8, s16, v80
	v_fmac_f32_e32 v9, s16, v81
	global_load_dwordx4 v[78:81], v[6:7], off offset:-4096
	s_waitcnt vmcnt(31)
	v_fmac_f32_e32 v10, s17, v82
	v_fmac_f32_e32 v11, s17, v83
	v_fmac_f32_e32 v8, s17, v84
	v_fmac_f32_e32 v9, s17, v85
	global_load_dwordx4 v[82:85], v[6:7], off
	v_lshl_add_u64 v[6:7], v[6:7], 0, vcc
	s_waitcnt vmcnt(31)
	v_fmac_f32_e32 v10, s38, v86
	v_fmac_f32_e32 v11, s38, v87
	v_fmac_f32_e32 v8, s38, v88
	v_fmac_f32_e32 v9, s38, v89
	global_load_dwordx4 v[86:89], v[6:7], off offset:-4096
	s_waitcnt vmcnt(31)
	v_fmac_f32_e32 v10, s39, v90
	v_fmac_f32_e32 v11, s39, v91
	v_fmac_f32_e32 v8, s39, v92
	v_fmac_f32_e32 v9, s39, v93
	global_load_dwordx4 v[90:93], v[6:7], off
	v_lshl_add_u64 v[6:7], v[6:7], 0, vcc
	v_readlane_b32 s16, v143, 20
	v_readlane_b32 s17, v143, 21
	v_readlane_b32 s38, v143, 22
	v_readlane_b32 s39, v143, 23
	s_waitcnt vmcnt(31)
; DEVI void convert_layer(const Params& p, int layer, char* smem) {
;     ...
;         for (int d = 0; d < 128; ++d) {
;           const float a = pwr[d] * ps[g * 128 + d];
;           const f32x4 w4 = *(const f32x4*)(wor + (size_t)d * 1024);
;           acc = acc + w4 * a;
;         }
	v_fmac_f32_e32 v10, s16, v94
	v_fmac_f32_e32 v11, s16, v95
	v_fmac_f32_e32 v8, s16, v96
	v_fmac_f32_e32 v9, s16, v97
	global_load_dwordx4 v[94:97], v[6:7], off offset:-4096
	s_waitcnt vmcnt(31)
	v_fmac_f32_e32 v10, s17, v98
	v_fmac_f32_e32 v11, s17, v99
	v_fmac_f32_e32 v8, s17, v100
	v_fmac_f32_e32 v9, s17, v101
	global_load_dwordx4 v[98:101], v[6:7], off
	v_lshl_add_u64 v[6:7], v[6:7], 0, vcc
	s_waitcnt vmcnt(31)
	v_fmac_f32_e32 v10, s38, v102
	v_fmac_f32_e32 v11, s38, v103
	v_fmac_f32_e32 v8, s38, v104
	v_fmac_f32_e32 v9, s38, v105
	global_load_dwordx4 v[102:105], v[6:7], off offset:-4096
	s_waitcnt vmcnt(31)
	v_fmac_f32_e32 v10, s39, v106
	v_fmac_f32_e32 v11, s39, v107
	v_fmac_f32_e32 v8, s39, v108
	v_fmac_f32_e32 v9, s39, v109
	global_load_dwordx4 v[106:109], v[6:7], off
	v_lshl_add_u64 v[6:7], v[6:7], 0, vcc
	v_readlane_b32 s16, v143, 24
	v_readlane_b32 s17, v143, 25
	v_readlane_b32 s38, v143, 26
	v_readlane_b32 s39, v143, 27
	s_waitcnt vmcnt(31)
	v_fmac_f32_e32 v10, s16, v110
	v_fmac_f32_e32 v11, s16, v111
	v_fmac_f32_e32 v8, s16, v112
	v_fmac_f32_e32 v9, s16, v113
	global_load_dwordx4 v[110:113], v[6:7], off offset:-4096
	s_waitcnt vmcnt(31)
	v_fmac_f32_e32 v10, s17, v114
	v_fmac_f32_e32 v11, s17, v115
	v_fmac_f32_e32 v8, s17, v116
	v_fmac_f32_e32 v9, s17, v117
	global_load_dwordx4 v[114:117], v[6:7], off
	v_lshl_add_u64 v[6:7], v[6:7], 0, vcc
	s_waitcnt vmcnt(31)
	v_fmac_f32_e32 v10, s38, v118
	v_fmac_f32_e32 v11, s38, v119
	v_fmac_f32_e32 v8, s38, v120
	v_fmac_f32_e32 v9, s38, v121
	global_load_dwordx4 v[118:121], v[6:7], off offset:-4096
	s_waitcnt vmcnt(31)
	v_fmac_f32_e32 v10, s39, v122
	v_fmac_f32_e32 v11, s39, v123
	v_fmac_f32_e32 v8, s39, v124
	v_fmac_f32_e32 v9, s39, v125
	global_load_dwordx4 v[122:125], v[6:7], off
	v_lshl_add_u64 v[6:7], v[6:7], 0, vcc
	v_readlane_b32 s16, v143, 28
	v_readlane_b32 s17, v143, 29
	v_readlane_b32 s38, v143, 30
	v_readlane_b32 s39, v143, 31
	s_waitcnt vmcnt(31)
	v_fmac_f32_e32 v10, s16, v126
	v_fmac_f32_e32 v11, s16, v127
	v_fmac_f32_e32 v8, s16, v128
	v_fmac_f32_e32 v9, s16, v129
	global_load_dwordx4 v[126:129], v[6:7], off offset:-4096
	s_waitcnt vmcnt(31)
	v_fmac_f32_e32 v10, s17, v130
	v_fmac_f32_e32 v11, s17, v131
	v_fmac_f32_e32 v8, s17, v132
	v_fmac_f32_e32 v9, s17, v133
	global_load_dwordx4 v[130:133], v[6:7], off
	v_lshl_add_u64 v[6:7], v[6:7], 0, vcc
	s_waitcnt vmcnt(31)
	v_fmac_f32_e32 v10, s38, v134
	v_fmac_f32_e32 v11, s38, v135
	v_fmac_f32_e32 v8, s38, v136
	v_fmac_f32_e32 v9, s38, v137
	global_load_dwordx4 v[134:137], v[6:7], off offset:-4096
	s_waitcnt vmcnt(31)
	v_fmac_f32_e32 v10, s39, v138
	v_fmac_f32_e32 v11, s39, v139
	v_fmac_f32_e32 v8, s39, v140
	v_fmac_f32_e32 v9, s39, v141
	global_load_dwordx4 v[138:141], v[6:7], off
	v_lshl_add_u64 v[6:7], v[6:7], 0, vcc
	v_readlane_b32 s16, v143, 32
	v_readlane_b32 s17, v143, 33
	v_readlane_b32 s38, v143, 34
	v_readlane_b32 s39, v143, 35
	s_waitcnt vmcnt(31)
	v_fmac_f32_e32 v10, s16, v14
	v_fmac_f32_e32 v11, s16, v15
	v_fmac_f32_e32 v8, s16, v16
	v_fmac_f32_e32 v9, s16, v17
	s_waitcnt vmcnt(30)
	v_fmac_f32_e32 v10, s17, v18
	v_fmac_f32_e32 v11, s17, v19
	v_fmac_f32_e32 v8, s17, v20
	v_fmac_f32_e32 v9, s17, v21
	s_waitcnt vmcnt(29)
	v_fmac_f32_e32 v10, s38, v22
	v_fmac_f32_e32 v11, s38, v23
	v_fmac_f32_e32 v8, s38, v24
	v_fmac_f32_e32 v9, s38, v25
	s_waitcnt vmcnt(28)
	v_fmac_f32_e32 v10, s39, v26
	v_fmac_f32_e32 v11, s39, v27
	v_fmac_f32_e32 v8, s39, v28
	v_fmac_f32_e32 v9, s39, v29
	v_readlane_b32 s16, v143, 36
	v_readlane_b32 s17, v143, 37
	v_readlane_b32 s38, v143, 38
	v_readlane_b32 s39, v143, 39
	s_waitcnt vmcnt(27)
	v_fmac_f32_e32 v10, s16, v30
	v_fmac_f32_e32 v11, s16, v31
	v_fmac_f32_e32 v8, s16, v32
	v_fmac_f32_e32 v9, s16, v33
	s_waitcnt vmcnt(26)
	v_fmac_f32_e32 v10, s17, v34
	v_fmac_f32_e32 v11, s17, v35
	v_fmac_f32_e32 v8, s17, v36
	v_fmac_f32_e32 v9, s17, v37
	s_waitcnt vmcnt(25)
	v_fmac_f32_e32 v10, s38, v38
	v_fmac_f32_e32 v11, s38, v39
	v_fmac_f32_e32 v8, s38, v40
	v_fmac_f32_e32 v9, s38, v41
	s_waitcnt vmcnt(24)
	v_fmac_f32_e32 v10, s39, v42
	v_fmac_f32_e32 v11, s39, v43
	v_fmac_f32_e32 v8, s39, v44
	v_fmac_f32_e32 v9, s39, v45
	v_readlane_b32 s16, v143, 40
	v_readlane_b32 s17, v143, 41
	v_readlane_b32 s38, v143, 42
	v_readlane_b32 s39, v143, 43
	s_waitcnt vmcnt(23)
	v_fmac_f32_e32 v10, s16, v46
	v_fmac_f32_e32 v11, s16, v47
	v_fmac_f32_e32 v8, s16, v48
	v_fmac_f32_e32 v9, s16, v49
	s_waitcnt vmcnt(22)
	v_fmac_f32_e32 v10, s17, v50
	v_fmac_f32_e32 v11, s17, v51
	v_fmac_f32_e32 v8, s17, v52
	v_fmac_f32_e32 v9, s17, v53
	s_waitcnt vmcnt(21)
; DEVI bf16_t f2bf(float a) { return (bf16_t)(pack2(a, 0.f) & 0xffff); }
; DEVI void convert_layer(const Params& p, int layer, char* smem) {
;     ...
; #pragma unroll 8
;         for (int d = 0; d < 128; ++d) {
;           const float a = pwr[d] * ps[g * 128 + d];
;           const f32x4 w4 = *(const f32x4*)(wor + (size_t)d * 1024);
;           acc = acc + w4 * a;
;         }
; #pragma unroll
;         for (int e = 0; e < 4; ++e) wb[WB_OUT + wfm(tid * 4 + e, 512 + item, 1024)] = f2bf(acc[e]);
	v_fmac_f32_e32 v10, s38, v54
	v_fmac_f32_e32 v11, s38, v55
	v_fmac_f32_e32 v8, s38, v56
	v_fmac_f32_e32 v9, s38, v57
	s_waitcnt vmcnt(20)
	v_fmac_f32_e32 v10, s39, v58
	v_fmac_f32_e32 v11, s39, v59
	v_fmac_f32_e32 v8, s39, v60
	v_fmac_f32_e32 v9, s39, v61
	v_readlane_b32 s16, v143, 44
	v_readlane_b32 s17, v143, 45
	v_readlane_b32 s38, v143, 46
	v_readlane_b32 s39, v143, 47
	s_waitcnt vmcnt(19)
	v_fmac_f32_e32 v10, s16, v62
	v_fmac_f32_e32 v11, s16, v63
	v_fmac_f32_e32 v8, s16, v64
	v_fmac_f32_e32 v9, s16, v65
	s_waitcnt vmcnt(18)
	v_fmac_f32_e32 v10, s17, v66
	v_fmac_f32_e32 v11, s17, v67
	v_fmac_f32_e32 v8, s17, v68
	v_fmac_f32_e32 v9, s17, v69
	s_waitcnt vmcnt(17)
	v_fmac_f32_e32 v10, s38, v70
	v_fmac_f32_e32 v11, s38, v71
	v_fmac_f32_e32 v8, s38, v72
	v_fmac_f32_e32 v9, s38, v73
	s_waitcnt vmcnt(16)
	v_fmac_f32_e32 v10, s39, v74
	v_fmac_f32_e32 v11, s39, v75
	v_fmac_f32_e32 v8, s39, v76
	v_fmac_f32_e32 v9, s39, v77
	v_readlane_b32 s16, v143, 48
	v_readlane_b32 s17, v143, 49
	v_readlane_b32 s38, v143, 50
	v_readlane_b32 s39, v143, 51
	s_waitcnt vmcnt(15)
	v_fmac_f32_e32 v10, s16, v78
	v_fmac_f32_e32 v11, s16, v79
	v_fmac_f32_e32 v8, s16, v80
	v_fmac_f32_e32 v9, s16, v81
	s_waitcnt vmcnt(14)
	v_fmac_f32_e32 v10, s17, v82
	v_fmac_f32_e32 v11, s17, v83
	v_fmac_f32_e32 v8, s17, v84
	v_fmac_f32_e32 v9, s17, v85
	s_waitcnt vmcnt(13)
	v_fmac_f32_e32 v10, s38, v86
	v_fmac_f32_e32 v11, s38, v87
	v_fmac_f32_e32 v8, s38, v88
	v_fmac_f32_e32 v9, s38, v89
	s_waitcnt vmcnt(12)
	v_fmac_f32_e32 v10, s39, v90
	v_fmac_f32_e32 v11, s39, v91
	v_fmac_f32_e32 v8, s39, v92
	v_fmac_f32_e32 v9, s39, v93
	v_readlane_b32 s16, v143, 52
	v_readlane_b32 s17, v143, 53
	v_readlane_b32 s38, v143, 54
	v_readlane_b32 s39, v143, 55
	s_waitcnt vmcnt(11)
	v_fmac_f32_e32 v10, s16, v94
	v_fmac_f32_e32 v11, s16, v95
	v_fmac_f32_e32 v8, s16, v96
	v_fmac_f32_e32 v9, s16, v97
	s_waitcnt vmcnt(10)
	v_fmac_f32_e32 v10, s17, v98
	v_fmac_f32_e32 v11, s17, v99
	v_fmac_f32_e32 v8, s17, v100
	v_fmac_f32_e32 v9, s17, v101
	s_waitcnt vmcnt(9)
	v_fmac_f32_e32 v10, s38, v102
	v_fmac_f32_e32 v11, s38, v103
	v_fmac_f32_e32 v8, s38, v104
	v_fmac_f32_e32 v9, s38, v105
	s_waitcnt vmcnt(8)
	v_fmac_f32_e32 v10, s39, v106
	v_fmac_f32_e32 v11, s39, v107
	v_fmac_f32_e32 v8, s39, v108
	v_fmac_f32_e32 v9, s39, v109
	v_readlane_b32 s16, v143, 56
	v_readlane_b32 s17, v143, 57
	v_readlane_b32 s38, v143, 58
	v_readlane_b32 s39, v143, 59
	s_waitcnt vmcnt(7)
	v_fmac_f32_e32 v10, s16, v110
	v_fmac_f32_e32 v11, s16, v111
	v_fmac_f32_e32 v8, s16, v112
	v_fmac_f32_e32 v9, s16, v113
	s_waitcnt vmcnt(6)
	v_fmac_f32_e32 v10, s17, v114
	v_fmac_f32_e32 v11, s17, v115
	v_fmac_f32_e32 v8, s17, v116
	v_fmac_f32_e32 v9, s17, v117
	s_waitcnt vmcnt(5)
	v_fmac_f32_e32 v10, s38, v118
	v_fmac_f32_e32 v11, s38, v119
	v_fmac_f32_e32 v8, s38, v120
	v_fmac_f32_e32 v9, s38, v121
	s_waitcnt vmcnt(4)
	v_fmac_f32_e32 v10, s39, v122
	v_fmac_f32_e32 v11, s39, v123
	v_fmac_f32_e32 v8, s39, v124
	v_fmac_f32_e32 v9, s39, v125
	v_readlane_b32 s16, v143, 60
	v_readlane_b32 s17, v143, 61
	v_readlane_b32 s38, v143, 62
	v_readlane_b32 s39, v143, 63
	s_waitcnt vmcnt(3)
	v_fmac_f32_e32 v10, s16, v126
	v_fmac_f32_e32 v11, s16, v127
	v_fmac_f32_e32 v8, s16, v128
	v_fmac_f32_e32 v9, s16, v129
	s_waitcnt vmcnt(2)
	v_fmac_f32_e32 v10, s17, v130
	v_fmac_f32_e32 v11, s17, v131
	v_fmac_f32_e32 v8, s17, v132
	v_fmac_f32_e32 v9, s17, v133
	s_waitcnt vmcnt(1)
	v_fmac_f32_e32 v10, s38, v134
	v_fmac_f32_e32 v11, s38, v135
	v_fmac_f32_e32 v8, s38, v136
	v_fmac_f32_e32 v9, s38, v137
	s_waitcnt vmcnt(0)
	v_fmac_f32_e32 v10, s39, v138
	v_fmac_f32_e32 v11, s39, v139
	v_fmac_f32_e32 v8, s39, v140
	v_fmac_f32_e32 v9, s39, v141
	s_add_i32 s16, s1, 0x200
	s_ashr_i32 s16, s16, 5
	s_ashr_i32 s17, s16, 31
	s_lshl_b32 s25, s1, 1
	v_and_or_b32 v0, s25, 48, v12
	s_and_b32 s25, s1, 7
	s_lshl_b64 s[16:17], s[16:17], 10
	v_lshl_add_u64 v[6:7], v[2:3], 0, s[16:17]
	s_lshl_b32 s62, s25, 1
	v_lshl_add_u64 v[6:7], v[6:7], 0, s[62:63]
	v_lshlrev_b32_e32 v0, 4, v0
	v_lshl_add_u64 v[6:7], v[6:7], 0, v[0:1]
	s_mov_b32 s16, 0x840000
	v_add_co_u32_e32 v6, vcc, s16, v6
	v_cvt_pk_bf16_f32 v0, v11, s0
	s_nop 0
	v_addc_co_u32_e32 v7, vcc, 0, v7, vcc
	v_readlane_b32 s16, v248, 48
	global_store_short v[6:7], v0, off offset:16
	v_cvt_pk_bf16_f32 v0, v8, s0
	s_add_i32 s1, s1, s48
	s_add_i32 s13, s13, s16
	v_cvt_pk_bf16_f32 v10, v10, s0
	global_store_short v[6:7], v0, off offset:32
	v_cvt_pk_bf16_f32 v0, v9, s0
	s_cmpk_gt_i32 s1, 0x1ff
	global_store_short v[6:7], v10, off
	global_store_short v[6:7], v0, off offset:48
	s_cbranch_scc0 .LBB0_1679

; #define BIDX opaque_bid()
; DEVI void convert_layer(const Params& p, int layer, char* smem) {
;     ...
;       for (int item = BIDX; item < 512; item += gridDim.x) {
;         const int g = item >> 7, c = item & 127;
;         const float* pwr = pw + ((size_t)g * 128 + c) * 128;
;         const float* wor = wo + (size_t)(512 + g * 128) * 1024 + tid * 4;
;         f32x4 acc = f32x4{0.f, 0.f, 0.f, 0.f};
; #pragma unroll 8
;         for (int d = 0; d < 128; ++d) {
;           const float a = pwr[d] * ps[g * 128 + d];
;           const f32x4 w4 = *(const f32x4*)(wor + (size_t)d * 1024);
;           acc = acc + w4 * a;
;         }
.LBB0_1977:
	v_and_b32_e32 v0, 63, v206
	v_lshlrev_b32_e32 v0, 2, v0
	s_mov_b32 s16, s10
	s_mov_b32 s17, s11
	global_load_dword v142, v0, s[16:17]
	global_load_dword v143, v0, s[16:17] offset:256
	s_mov_b32 s16, s7
	s_mov_b32 s17, s9
	global_load_dword v144, v0, s[16:17]
	global_load_dword v145, v0, s[16:17] offset:256
	s_mov_b32 s0, 0xffffa000
	s_mov_b32 s1, -1
	v_lshl_add_u64 v[10:11], v[10:11], 0, s[0:1]
	s_mov_b64 vcc, 0x2000
	global_load_dwordx4 v[14:17], v[10:11], off offset:-4096
	global_load_dwordx4 v[18:21], v[10:11], off
	v_lshl_add_u64 v[10:11], v[10:11], 0, vcc
	global_load_dwordx4 v[22:25], v[10:11], off offset:-4096
	global_load_dwordx4 v[26:29], v[10:11], off
	v_lshl_add_u64 v[10:11], v[10:11], 0, vcc
	global_load_dwordx4 v[30:33], v[10:11], off offset:-4096
	global_load_dwordx4 v[34:37], v[10:11], off
	v_lshl_add_u64 v[10:11], v[10:11], 0, vcc
	global_load_dwordx4 v[38:41], v[10:11], off offset:-4096
	global_load_dwordx4 v[42:45], v[10:11], off
	v_lshl_add_u64 v[10:11], v[10:11], 0, vcc
	global_load_dwordx4 v[46:49], v[10:11], off offset:-4096
	global_load_dwordx4 v[50:53], v[10:11], off
	v_lshl_add_u64 v[10:11], v[10:11], 0, vcc
	global_load_dwordx4 v[54:57], v[10:11], off offset:-4096
	global_load_dwordx4 v[58:61], v[10:11], off
	v_lshl_add_u64 v[10:11], v[10:11], 0, vcc
	global_load_dwordx4 v[62:65], v[10:11], off offset:-4096
	global_load_dwordx4 v[66:69], v[10:11], off
	v_lshl_add_u64 v[10:11], v[10:11], 0, vcc
	global_load_dwordx4 v[70:73], v[10:11], off offset:-4096
	global_load_dwordx4 v[74:77], v[10:11], off
	v_lshl_add_u64 v[10:11], v[10:11], 0, vcc
	global_load_dwordx4 v[78:81], v[10:11], off offset:-4096
	global_load_dwordx4 v[82:85], v[10:11], off
	v_lshl_add_u64 v[10:11], v[10:11], 0, vcc
	global_load_dwordx4 v[86:89], v[10:11], off offset:-4096
	global_load_dwordx4 v[90:93], v[10:11], off
	v_lshl_add_u64 v[10:11], v[10:11], 0, vcc
	global_load_dwordx4 v[94:97], v[10:11], off offset:-4096
	global_load_dwordx4 v[98:101], v[10:11], off
	v_lshl_add_u64 v[10:11], v[10:11], 0, vcc
	global_load_dwordx4 v[102:105], v[10:11], off offset:-4096
	global_load_dwordx4 v[106:109], v[10:11], off
	v_lshl_add_u64 v[10:11], v[10:11], 0, vcc
	global_load_dwordx4 v[110:113], v[10:11], off offset:-4096
	global_load_dwordx4 v[114:117], v[10:11], off
	v_lshl_add_u64 v[10:11], v[10:11], 0, vcc
	global_load_dwordx4 v[118:121], v[10:11], off offset:-4096
	global_load_dwordx4 v[122:125], v[10:11], off
	v_lshl_add_u64 v[10:11], v[10:11], 0, vcc
	global_load_dwordx4 v[126:129], v[10:11], off offset:-4096
	global_load_dwordx4 v[130:133], v[10:11], off
	v_lshl_add_u64 v[10:11], v[10:11], 0, vcc
	global_load_dwordx4 v[134:137], v[10:11], off offset:-4096
	global_load_dwordx4 v[138:141], v[10:11], off
	v_lshl_add_u64 v[10:11], v[10:11], 0, vcc
	s_waitcnt vmcnt(32)
	v_mul_f32_e32 v142, v142, v144
	v_mul_f32_e32 v143, v143, v145
	s_nop 1
	v_readlane_b32 s0, v142, 0
	v_readlane_b32 s1, v142, 1
	v_readlane_b32 s16, v142, 2
	v_readlane_b32 s17, v142, 3
	s_waitcnt vmcnt(31)
	v_fmac_f32_e32 v8, s0, v14
	v_fmac_f32_e32 v9, s0, v15
	v_fmac_f32_e32 v6, s0, v16
	v_fmac_f32_e32 v7, s0, v17
	global_load_dwordx4 v[14:17], v[10:11], off offset:-4096
	s_waitcnt vmcnt(31)
	v_fmac_f32_e32 v8, s1, v18
	v_fmac_f32_e32 v9, s1, v19
	v_fmac_f32_e32 v6, s1, v20
	v_fmac_f32_e32 v7, s1, v21
	global_load_dwordx4 v[18:21], v[10:11], off
	v_lshl_add_u64 v[10:11], v[10:11], 0, vcc
	s_waitcnt vmcnt(31)
	v_fmac_f32_e32 v8, s16, v22
	v_fmac_f32_e32 v9, s16, v23
	v_fmac_f32_e32 v6, s16, v24
	v_fmac_f32_e32 v7, s16, v25
	global_load_dwordx4 v[22:25], v[10:11], off offset:-4096
	s_waitcnt vmcnt(31)
	v_fmac_f32_e32 v8, s17, v26
	v_fmac_f32_e32 v9, s17, v27
	v_fmac_f32_e32 v6, s17, v28
	v_fmac_f32_e32 v7, s17, v29
	global_load_dwordx4 v[26:29], v[10:11], off
	v_lshl_add_u64 v[10:11], v[10:11], 0, vcc
	v_readlane_b32 s0, v142, 4
	v_readlane_b32 s1, v142, 5
	v_readlane_b32 s16, v142, 6
	v_readlane_b32 s17, v142, 7
	s_waitcnt vmcnt(31)
	v_fmac_f32_e32 v8, s0, v30
	v_fmac_f32_e32 v9, s0, v31
	v_fmac_f32_e32 v6, s0, v32
	v_fmac_f32_e32 v7, s0, v33
	global_load_dwordx4 v[30:33], v[10:11], off offset:-4096
	s_waitcnt vmcnt(31)
	v_fmac_f32_e32 v8, s1, v34
	v_fmac_f32_e32 v9, s1, v35
	v_fmac_f32_e32 v6, s1, v36
	v_fmac_f32_e32 v7, s1, v37
	global_load_dwordx4 v[34:37], v[10:11], off
	v_lshl_add_u64 v[10:11], v[10:11], 0, vcc
	s_waitcnt vmcnt(31)
	v_fmac_f32_e32 v8, s16, v38
	v_fmac_f32_e32 v9, s16, v39
	v_fmac_f32_e32 v6, s16, v40
	v_fmac_f32_e32 v7, s16, v41
	global_load_dwordx4 v[38:41], v[10:11], off offset:-4096
	s_waitcnt vmcnt(31)
	v_fmac_f32_e32 v8, s17, v42
	v_fmac_f32_e32 v9, s17, v43
	v_fmac_f32_e32 v6, s17, v44
	v_fmac_f32_e32 v7, s17, v45
	global_load_dwordx4 v[42:45], v[10:11], off
	v_lshl_add_u64 v[10:11], v[10:11], 0, vcc
	v_readlane_b32 s0, v142, 8
	v_readlane_b32 s1, v142, 9
	v_readlane_b32 s16, v142, 10
	v_readlane_b32 s17, v142, 11
	s_waitcnt vmcnt(31)
	v_fmac_f32_e32 v8, s0, v46
	v_fmac_f32_e32 v9, s0, v47
	v_fmac_f32_e32 v6, s0, v48
	v_fmac_f32_e32 v7, s0, v49
	global_load_dwordx4 v[46:49], v[10:11], off offset:-4096
	s_waitcnt vmcnt(31)
	v_fmac_f32_e32 v8, s1, v50
	v_fmac_f32_e32 v9, s1, v51
	v_fmac_f32_e32 v6, s1, v52
	v_fmac_f32_e32 v7, s1, v53
	global_load_dwordx4 v[50:53], v[10:11], off
	v_lshl_add_u64 v[10:11], v[10:11], 0, vcc
	s_waitcnt vmcnt(31)
	v_fmac_f32_e32 v8, s16, v54
	v_fmac_f32_e32 v9, s16, v55
	v_fmac_f32_e32 v6, s16, v56
	v_fmac_f32_e32 v7, s16, v57
	global_load_dwordx4 v[54:57], v[10:11], off offset:-4096
	s_waitcnt vmcnt(31)
; DEVI void convert_layer(const Params& p, int layer, char* smem) {
;     ...
;         const float* pwr = pw + ((size_t)g * 128 + c) * 128;
;         const float* wor = wo + (size_t)(512 + g * 128) * 1024 + tid * 4;
;         f32x4 acc = f32x4{0.f, 0.f, 0.f, 0.f};
; #pragma unroll 8
;         for (int d = 0; d < 128; ++d) {
;           const float a = pwr[d] * ps[g * 128 + d];
;           const f32x4 w4 = *(const f32x4*)(wor + (size_t)d * 1024);
;           acc = acc + w4 * a;
;         }
	v_fmac_f32_e32 v8, s17, v58
	v_fmac_f32_e32 v9, s17, v59
	v_fmac_f32_e32 v6, s17, v60
	v_fmac_f32_e32 v7, s17, v61
	global_load_dwordx4 v[58:61], v[10:11], off
	v_lshl_add_u64 v[10:11], v[10:11], 0, vcc
	v_readlane_b32 s0, v142, 12
	v_readlane_b32 s1, v142, 13
	v_readlane_b32 s16, v142, 14
	v_readlane_b32 s17, v142, 15
	s_waitcnt vmcnt(31)
	v_fmac_f32_e32 v8, s0, v62
	v_fmac_f32_e32 v9, s0, v63
	v_fmac_f32_e32 v6, s0, v64
	v_fmac_f32_e32 v7, s0, v65
	global_load_dwordx4 v[62:65], v[10:11], off offset:-4096
	s_waitcnt vmcnt(31)
	v_fmac_f32_e32 v8, s1, v66
	v_fmac_f32_e32 v9, s1, v67
	v_fmac_f32_e32 v6, s1, v68
	v_fmac_f32_e32 v7, s1, v69
	global_load_dwordx4 v[66:69], v[10:11], off
	v_lshl_add_u64 v[10:11], v[10:11], 0, vcc
	s_waitcnt vmcnt(31)
	v_fmac_f32_e32 v8, s16, v70
	v_fmac_f32_e32 v9, s16, v71
	v_fmac_f32_e32 v6, s16, v72
	v_fmac_f32_e32 v7, s16, v73
	global_load_dwordx4 v[70:73], v[10:11], off offset:-4096
	s_waitcnt vmcnt(31)
	v_fmac_f32_e32 v8, s17, v74
	v_fmac_f32_e32 v9, s17, v75
	v_fmac_f32_e32 v6, s17, v76
	v_fmac_f32_e32 v7, s17, v77
	global_load_dwordx4 v[74:77], v[10:11], off
	v_lshl_add_u64 v[10:11], v[10:11], 0, vcc
	v_readlane_b32 s0, v142, 16
	v_readlane_b32 s1, v142, 17
	v_readlane_b32 s16, v142, 18
	v_readlane_b32 s17, v142, 19
	s_waitcnt vmcnt(31)
	v_fmac_f32_e32 v8, s0, v78
	v_fmac_f32_e32 v9, s0, v79
	v_fmac_f32_e32 v6, s0, v80
	v_fmac_f32_e32 v7, s0, v81
	global_load_dwordx4 v[78:81], v[10:11], off offset:-4096
	s_waitcnt vmcnt(31)
	v_fmac_f32_e32 v8, s1, v82
	v_fmac_f32_e32 v9, s1, v83
	v_fmac_f32_e32 v6, s1, v84
	v_fmac_f32_e32 v7, s1, v85
	global_load_dwordx4 v[82:85], v[10:11], off
	v_lshl_add_u64 v[10:11], v[10:11], 0, vcc
	s_waitcnt vmcnt(31)
	v_fmac_f32_e32 v8, s16, v86
	v_fmac_f32_e32 v9, s16, v87
	v_fmac_f32_e32 v6, s16, v88
	v_fmac_f32_e32 v7, s16, v89
	global_load_dwordx4 v[86:89], v[10:11], off offset:-4096
	s_waitcnt vmcnt(31)
	v_fmac_f32_e32 v8, s17, v90
	v_fmac_f32_e32 v9, s17, v91
	v_fmac_f32_e32 v6, s17, v92
	v_fmac_f32_e32 v7, s17, v93
	global_load_dwordx4 v[90:93], v[10:11], off
	v_lshl_add_u64 v[10:11], v[10:11], 0, vcc
	v_readlane_b32 s0, v142, 20
	v_readlane_b32 s1, v142, 21
	v_readlane_b32 s16, v142, 22
	v_readlane_b32 s17, v142, 23
	s_waitcnt vmcnt(31)
	v_fmac_f32_e32 v8, s0, v94
	v_fmac_f32_e32 v9, s0, v95
	v_fmac_f32_e32 v6, s0, v96
	v_fmac_f32_e32 v7, s0, v97
	global_load_dwordx4 v[94:97], v[10:11], off offset:-4096
	s_waitcnt vmcnt(31)
	v_fmac_f32_e32 v8, s1, v98
	v_fmac_f32_e32 v9, s1, v99
	v_fmac_f32_e32 v6, s1, v100
	v_fmac_f32_e32 v7, s1, v101
	global_load_dwordx4 v[98:101], v[10:11], off
	v_lshl_add_u64 v[10:11], v[10:11], 0, vcc
	s_waitcnt vmcnt(31)
	v_fmac_f32_e32 v8, s16, v102
	v_fmac_f32_e32 v9, s16, v103
	v_fmac_f32_e32 v6, s16, v104
	v_fmac_f32_e32 v7, s16, v105
	global_load_dwordx4 v[102:105], v[10:11], off offset:-4096
	s_waitcnt vmcnt(31)
	v_fmac_f32_e32 v8, s17, v106
	v_fmac_f32_e32 v9, s17, v107
	v_fmac_f32_e32 v6, s17, v108
	v_fmac_f32_e32 v7, s17, v109
	global_load_dwordx4 v[106:109], v[10:11], off
	v_lshl_add_u64 v[10:11], v[10:11], 0, vcc
	v_readlane_b32 s0, v142, 24
	v_readlane_b32 s1, v142, 25
	v_readlane_b32 s16, v142, 26
	v_readlane_b32 s17, v142, 27
	s_waitcnt vmcnt(31)
	v_fmac_f32_e32 v8, s0, v110
	v_fmac_f32_e32 v9, s0, v111
	v_fmac_f32_e32 v6, s0, v112
	v_fmac_f32_e32 v7, s0, v113
	global_load_dwordx4 v[110:113], v[10:11], off offset:-4096
	s_waitcnt vmcnt(31)
	v_fmac_f32_e32 v8, s1, v114
	v_fmac_f32_e32 v9, s1, v115
	v_fmac_f32_e32 v6, s1, v116
	v_fmac_f32_e32 v7, s1, v117
	global_load_dwordx4 v[114:117], v[10:11], off
	v_lshl_add_u64 v[10:11], v[10:11], 0, vcc
	s_waitcnt vmcnt(31)
	v_fmac_f32_e32 v8, s16, v118
	v_fmac_f32_e32 v9, s16, v119
	v_fmac_f32_e32 v6, s16, v120
	v_fmac_f32_e32 v7, s16, v121
	global_load_dwordx4 v[118:121], v[10:11], off offset:-4096
	s_waitcnt vmcnt(31)
	v_fmac_f32_e32 v8, s17, v122
	v_fmac_f32_e32 v9, s17, v123
	v_fmac_f32_e32 v6, s17, v124
	v_fmac_f32_e32 v7, s17, v125
	global_load_dwordx4 v[122:125], v[10:11], off
	v_lshl_add_u64 v[10:11], v[10:11], 0, vcc
	v_readlane_b32 s0, v142, 28
	v_readlane_b32 s1, v142, 29
	v_readlane_b32 s16, v142, 30
	v_readlane_b32 s17, v142, 31
	s_waitcnt vmcnt(31)
	v_fmac_f32_e32 v8, s0, v126
	v_fmac_f32_e32 v9, s0, v127
	v_fmac_f32_e32 v6, s0, v128
	v_fmac_f32_e32 v7, s0, v129
	global_load_dwordx4 v[126:129], v[10:11], off offset:-4096
	s_waitcnt vmcnt(31)
	v_fmac_f32_e32 v8, s1, v130
	v_fmac_f32_e32 v9, s1, v131
	v_fmac_f32_e32 v6, s1, v132
	v_fmac_f32_e32 v7, s1, v133
	global_load_dwordx4 v[130:133], v[10:11], off
	v_lshl_add_u64 v[10:11], v[10:11], 0, vcc
	s_waitcnt vmcnt(31)
	v_fmac_f32_e32 v8, s16, v134
	v_fmac_f32_e32 v9, s16, v135
	v_fmac_f32_e32 v6, s16, v136
	v_fmac_f32_e32 v7, s16, v137
	global_load_dwordx4 v[134:137], v[10:11], off offset:-4096
	s_waitcnt vmcnt(31)
	v_fmac_f32_e32 v8, s17, v138
	v_fmac_f32_e32 v9, s17, v139
	v_fmac_f32_e32 v6, s17, v140
	v_fmac_f32_e32 v7, s17, v141
	global_load_dwordx4 v[138:141], v[10:11], off
	v_lshl_add_u64 v[10:11], v[10:11], 0, vcc
	v_readlane_b32 s0, v142, 32
	v_readlane_b32 s1, v142, 33
	v_readlane_b32 s16, v142, 34
	v_readlane_b32 s17, v142, 35
	s_waitcnt vmcnt(31)
	v_fmac_f32_e32 v8, s0, v14
	v_fmac_f32_e32 v9, s0, v15
	v_fmac_f32_e32 v6, s0, v16
	v_fmac_f32_e32 v7, s0, v17
	global_load_dwordx4 v[14:17], v[10:11], off offset:-4096
	s_waitcnt vmcnt(31)
	v_fmac_f32_e32 v8, s1, v18
	v_fmac_f32_e32 v9, s1, v19
	v_fmac_f32_e32 v6, s1, v20
	v_fmac_f32_e32 v7, s1, v21
	global_load_dwordx4 v[18:21], v[10:11], off
	v_lshl_add_u64 v[10:11], v[10:11], 0, vcc
	s_waitcnt vmcnt(31)
; DEVI void convert_layer(const Params& p, int layer, char* smem) {
;     ...
;         const float* pwr = pw + ((size_t)g * 128 + c) * 128;
;         const float* wor = wo + (size_t)(512 + g * 128) * 1024 + tid * 4;
;         f32x4 acc = f32x4{0.f, 0.f, 0.f, 0.f};
; #pragma unroll 8
;         for (int d = 0; d < 128; ++d) {
;           const float a = pwr[d] * ps[g * 128 + d];
;           const f32x4 w4 = *(const f32x4*)(wor + (size_t)d * 1024);
;           acc = acc + w4 * a;
;         }
	v_fmac_f32_e32 v8, s16, v22
	v_fmac_f32_e32 v9, s16, v23
	v_fmac_f32_e32 v6, s16, v24
	v_fmac_f32_e32 v7, s16, v25
	global_load_dwordx4 v[22:25], v[10:11], off offset:-4096
	s_waitcnt vmcnt(31)
	v_fmac_f32_e32 v8, s17, v26
	v_fmac_f32_e32 v9, s17, v27
	v_fmac_f32_e32 v6, s17, v28
	v_fmac_f32_e32 v7, s17, v29
	global_load_dwordx4 v[26:29], v[10:11], off
	v_lshl_add_u64 v[10:11], v[10:11], 0, vcc
	v_readlane_b32 s0, v142, 36
	v_readlane_b32 s1, v142, 37
	v_readlane_b32 s16, v142, 38
	v_readlane_b32 s17, v142, 39
	s_waitcnt vmcnt(31)
	v_fmac_f32_e32 v8, s0, v30
	v_fmac_f32_e32 v9, s0, v31
	v_fmac_f32_e32 v6, s0, v32
	v_fmac_f32_e32 v7, s0, v33
	global_load_dwordx4 v[30:33], v[10:11], off offset:-4096
	s_waitcnt vmcnt(31)
	v_fmac_f32_e32 v8, s1, v34
	v_fmac_f32_e32 v9, s1, v35
	v_fmac_f32_e32 v6, s1, v36
	v_fmac_f32_e32 v7, s1, v37
	global_load_dwordx4 v[34:37], v[10:11], off
	v_lshl_add_u64 v[10:11], v[10:11], 0, vcc
	s_waitcnt vmcnt(31)
	v_fmac_f32_e32 v8, s16, v38
	v_fmac_f32_e32 v9, s16, v39
	v_fmac_f32_e32 v6, s16, v40
	v_fmac_f32_e32 v7, s16, v41
	global_load_dwordx4 v[38:41], v[10:11], off offset:-4096
	s_waitcnt vmcnt(31)
	v_fmac_f32_e32 v8, s17, v42
	v_fmac_f32_e32 v9, s17, v43
	v_fmac_f32_e32 v6, s17, v44
	v_fmac_f32_e32 v7, s17, v45
	global_load_dwordx4 v[42:45], v[10:11], off
	v_lshl_add_u64 v[10:11], v[10:11], 0, vcc
	v_readlane_b32 s0, v142, 40
	v_readlane_b32 s1, v142, 41
	v_readlane_b32 s16, v142, 42
	v_readlane_b32 s17, v142, 43
	s_waitcnt vmcnt(31)
	v_fmac_f32_e32 v8, s0, v46
	v_fmac_f32_e32 v9, s0, v47
	v_fmac_f32_e32 v6, s0, v48
	v_fmac_f32_e32 v7, s0, v49
	global_load_dwordx4 v[46:49], v[10:11], off offset:-4096
	s_waitcnt vmcnt(31)
	v_fmac_f32_e32 v8, s1, v50
	v_fmac_f32_e32 v9, s1, v51
	v_fmac_f32_e32 v6, s1, v52
	v_fmac_f32_e32 v7, s1, v53
	global_load_dwordx4 v[50:53], v[10:11], off
	v_lshl_add_u64 v[10:11], v[10:11], 0, vcc
	s_waitcnt vmcnt(31)
	v_fmac_f32_e32 v8, s16, v54
	v_fmac_f32_e32 v9, s16, v55
	v_fmac_f32_e32 v6, s16, v56
	v_fmac_f32_e32 v7, s16, v57
	global_load_dwordx4 v[54:57], v[10:11], off offset:-4096
	s_waitcnt vmcnt(31)
	v_fmac_f32_e32 v8, s17, v58
	v_fmac_f32_e32 v9, s17, v59
	v_fmac_f32_e32 v6, s17, v60
	v_fmac_f32_e32 v7, s17, v61
	global_load_dwordx4 v[58:61], v[10:11], off
	v_lshl_add_u64 v[10:11], v[10:11], 0, vcc
	v_readlane_b32 s0, v142, 44
	v_readlane_b32 s1, v142, 45
	v_readlane_b32 s16, v142, 46
	v_readlane_b32 s17, v142, 47
	s_waitcnt vmcnt(31)
	v_fmac_f32_e32 v8, s0, v62
	v_fmac_f32_e32 v9, s0, v63
	v_fmac_f32_e32 v6, s0, v64
	v_fmac_f32_e32 v7, s0, v65
	global_load_dwordx4 v[62:65], v[10:11], off offset:-4096
	s_waitcnt vmcnt(31)
	v_fmac_f32_e32 v8, s1, v66
	v_fmac_f32_e32 v9, s1, v67
	v_fmac_f32_e32 v6, s1, v68
	v_fmac_f32_e32 v7, s1, v69
	global_load_dwordx4 v[66:69], v[10:11], off
	v_lshl_add_u64 v[10:11], v[10:11], 0, vcc
	s_waitcnt vmcnt(31)
	v_fmac_f32_e32 v8, s16, v70
	v_fmac_f32_e32 v9, s16, v71
	v_fmac_f32_e32 v6, s16, v72
	v_fmac_f32_e32 v7, s16, v73
	global_load_dwordx4 v[70:73], v[10:11], off offset:-4096
	s_waitcnt vmcnt(31)
	v_fmac_f32_e32 v8, s17, v74
	v_fmac_f32_e32 v9, s17, v75
	v_fmac_f32_e32 v6, s17, v76
	v_fmac_f32_e32 v7, s17, v77
	global_load_dwordx4 v[74:77], v[10:11], off
	v_lshl_add_u64 v[10:11], v[10:11], 0, vcc
	v_readlane_b32 s0, v142, 48
	v_readlane_b32 s1, v142, 49
	v_readlane_b32 s16, v142, 50
	v_readlane_b32 s17, v142, 51
	s_waitcnt vmcnt(31)
	v_fmac_f32_e32 v8, s0, v78
	v_fmac_f32_e32 v9, s0, v79
	v_fmac_f32_e32 v6, s0, v80
	v_fmac_f32_e32 v7, s0, v81
	global_load_dwordx4 v[78:81], v[10:11], off offset:-4096
	s_waitcnt vmcnt(31)
	v_fmac_f32_e32 v8, s1, v82
	v_fmac_f32_e32 v9, s1, v83
	v_fmac_f32_e32 v6, s1, v84
	v_fmac_f32_e32 v7, s1, v85
	global_load_dwordx4 v[82:85], v[10:11], off
	v_lshl_add_u64 v[10:11], v[10:11], 0, vcc
	s_waitcnt vmcnt(31)
	v_fmac_f32_e32 v8, s16, v86
	v_fmac_f32_e32 v9, s16, v87
	v_fmac_f32_e32 v6, s16, v88
	v_fmac_f32_e32 v7, s16, v89
	global_load_dwordx4 v[86:89], v[10:11], off offset:-4096
	s_waitcnt vmcnt(31)
	v_fmac_f32_e32 v8, s17, v90
	v_fmac_f32_e32 v9, s17, v91
	v_fmac_f32_e32 v6, s17, v92
	v_fmac_f32_e32 v7, s17, v93
	global_load_dwordx4 v[90:93], v[10:11], off
	v_lshl_add_u64 v[10:11], v[10:11], 0, vcc
	v_readlane_b32 s0, v142, 52
	v_readlane_b32 s1, v142, 53
	v_readlane_b32 s16, v142, 54
	v_readlane_b32 s17, v142, 55
	s_waitcnt vmcnt(31)
	v_fmac_f32_e32 v8, s0, v94
	v_fmac_f32_e32 v9, s0, v95
	v_fmac_f32_e32 v6, s0, v96
	v_fmac_f32_e32 v7, s0, v97
	global_load_dwordx4 v[94:97], v[10:11], off offset:-4096
	s_waitcnt vmcnt(31)
	v_fmac_f32_e32 v8, s1, v98
	v_fmac_f32_e32 v9, s1, v99
	v_fmac_f32_e32 v6, s1, v100
	v_fmac_f32_e32 v7, s1, v101
	global_load_dwordx4 v[98:101], v[10:11], off
	v_lshl_add_u64 v[10:11], v[10:11], 0, vcc
	s_waitcnt vmcnt(31)
	v_fmac_f32_e32 v8, s16, v102
	v_fmac_f32_e32 v9, s16, v103
	v_fmac_f32_e32 v6, s16, v104
	v_fmac_f32_e32 v7, s16, v105
	global_load_dwordx4 v[102:105], v[10:11], off offset:-4096
	s_waitcnt vmcnt(31)
	v_fmac_f32_e32 v8, s17, v106
	v_fmac_f32_e32 v9, s17, v107
	v_fmac_f32_e32 v6, s17, v108
	v_fmac_f32_e32 v7, s17, v109
	global_load_dwordx4 v[106:109], v[10:11], off
	v_lshl_add_u64 v[10:11], v[10:11], 0, vcc
	v_readlane_b32 s0, v142, 56
	v_readlane_b32 s1, v142, 57
	v_readlane_b32 s16, v142, 58
	v_readlane_b32 s17, v142, 59
	s_waitcnt vmcnt(31)
	v_fmac_f32_e32 v8, s0, v110
	v_fmac_f32_e32 v9, s0, v111
	v_fmac_f32_e32 v6, s0, v112
	v_fmac_f32_e32 v7, s0, v113
	global_load_dwordx4 v[110:113], v[10:11], off offset:-4096
	s_waitcnt vmcnt(31)
	v_fmac_f32_e32 v8, s1, v114
	v_fmac_f32_e32 v9, s1, v115
	v_fmac_f32_e32 v6, s1, v116
	v_fmac_f32_e32 v7, s1, v117
	global_load_dwordx4 v[114:117], v[10:11], off
	v_lshl_add_u64 v[10:11], v[10:11], 0, vcc
	s_waitcnt vmcnt(31)
; DEVI void convert_layer(const Params& p, int layer, char* smem) {
;     ...
;         const float* pwr = pw + ((size_t)g * 128 + c) * 128;
;         const float* wor = wo + (size_t)(512 + g * 128) * 1024 + tid * 4;
;         f32x4 acc = f32x4{0.f, 0.f, 0.f, 0.f};
; #pragma unroll 8
;         for (int d = 0; d < 128; ++d) {
;           const float a = pwr[d] * ps[g * 128 + d];
;           const f32x4 w4 = *(const f32x4*)(wor + (size_t)d * 1024);
;           acc = acc + w4 * a;
;         }
	v_fmac_f32_e32 v8, s16, v118
	v_fmac_f32_e32 v9, s16, v119
	v_fmac_f32_e32 v6, s16, v120
	v_fmac_f32_e32 v7, s16, v121
	global_load_dwordx4 v[118:121], v[10:11], off offset:-4096
	s_waitcnt vmcnt(31)
	v_fmac_f32_e32 v8, s17, v122
	v_fmac_f32_e32 v9, s17, v123
	v_fmac_f32_e32 v6, s17, v124
	v_fmac_f32_e32 v7, s17, v125
	global_load_dwordx4 v[122:125], v[10:11], off
	v_lshl_add_u64 v[10:11], v[10:11], 0, vcc
	v_readlane_b32 s0, v142, 60
	v_readlane_b32 s1, v142, 61
	v_readlane_b32 s16, v142, 62
	v_readlane_b32 s17, v142, 63
	s_waitcnt vmcnt(31)
	v_fmac_f32_e32 v8, s0, v126
	v_fmac_f32_e32 v9, s0, v127
	v_fmac_f32_e32 v6, s0, v128
	v_fmac_f32_e32 v7, s0, v129
	global_load_dwordx4 v[126:129], v[10:11], off offset:-4096
	s_waitcnt vmcnt(31)
	v_fmac_f32_e32 v8, s1, v130
	v_fmac_f32_e32 v9, s1, v131
	v_fmac_f32_e32 v6, s1, v132
	v_fmac_f32_e32 v7, s1, v133
	global_load_dwordx4 v[130:133], v[10:11], off
	v_lshl_add_u64 v[10:11], v[10:11], 0, vcc
	s_waitcnt vmcnt(31)
	v_fmac_f32_e32 v8, s16, v134
	v_fmac_f32_e32 v9, s16, v135
	v_fmac_f32_e32 v6, s16, v136
	v_fmac_f32_e32 v7, s16, v137
	global_load_dwordx4 v[134:137], v[10:11], off offset:-4096
	s_waitcnt vmcnt(31)
	v_fmac_f32_e32 v8, s17, v138
	v_fmac_f32_e32 v9, s17, v139
	v_fmac_f32_e32 v6, s17, v140
	v_fmac_f32_e32 v7, s17, v141
	global_load_dwordx4 v[138:141], v[10:11], off
	v_lshl_add_u64 v[10:11], v[10:11], 0, vcc
	v_readlane_b32 s0, v143, 0
	v_readlane_b32 s1, v143, 1
	v_readlane_b32 s16, v143, 2
	v_readlane_b32 s17, v143, 3
	s_waitcnt vmcnt(31)
	v_fmac_f32_e32 v8, s0, v14
	v_fmac_f32_e32 v9, s0, v15
	v_fmac_f32_e32 v6, s0, v16
	v_fmac_f32_e32 v7, s0, v17
	global_load_dwordx4 v[14:17], v[10:11], off offset:-4096
	s_waitcnt vmcnt(31)
	v_fmac_f32_e32 v8, s1, v18
	v_fmac_f32_e32 v9, s1, v19
	v_fmac_f32_e32 v6, s1, v20
	v_fmac_f32_e32 v7, s1, v21
	global_load_dwordx4 v[18:21], v[10:11], off
	v_lshl_add_u64 v[10:11], v[10:11], 0, vcc
	s_waitcnt vmcnt(31)
	v_fmac_f32_e32 v8, s16, v22
	v_fmac_f32_e32 v9, s16, v23
	v_fmac_f32_e32 v6, s16, v24
	v_fmac_f32_e32 v7, s16, v25
	global_load_dwordx4 v[22:25], v[10:11], off offset:-4096
	s_waitcnt vmcnt(31)
	v_fmac_f32_e32 v8, s17, v26
	v_fmac_f32_e32 v9, s17, v27
	v_fmac_f32_e32 v6, s17, v28
	v_fmac_f32_e32 v7, s17, v29
	global_load_dwordx4 v[26:29], v[10:11], off
	v_lshl_add_u64 v[10:11], v[10:11], 0, vcc
	v_readlane_b32 s0, v143, 4
	v_readlane_b32 s1, v143, 5
	v_readlane_b32 s16, v143, 6
	v_readlane_b32 s17, v143, 7
	s_waitcnt vmcnt(31)
	v_fmac_f32_e32 v8, s0, v30
	v_fmac_f32_e32 v9, s0, v31
	v_fmac_f32_e32 v6, s0, v32
	v_fmac_f32_e32 v7, s0, v33
	global_load_dwordx4 v[30:33], v[10:11], off offset:-4096
	s_waitcnt vmcnt(31)
	v_fmac_f32_e32 v8, s1, v34
	v_fmac_f32_e32 v9, s1, v35
	v_fmac_f32_e32 v6, s1, v36
	v_fmac_f32_e32 v7, s1, v37
	global_load_dwordx4 v[34:37], v[10:11], off
	v_lshl_add_u64 v[10:11], v[10:11], 0, vcc
	s_waitcnt vmcnt(31)
	v_fmac_f32_e32 v8, s16, v38
	v_fmac_f32_e32 v9, s16, v39
	v_fmac_f32_e32 v6, s16, v40
	v_fmac_f32_e32 v7, s16, v41
	global_load_dwordx4 v[38:41], v[10:11], off offset:-4096
	s_waitcnt vmcnt(31)
	v_fmac_f32_e32 v8, s17, v42
	v_fmac_f32_e32 v9, s17, v43
	v_fmac_f32_e32 v6, s17, v44
	v_fmac_f32_e32 v7, s17, v45
	global_load_dwordx4 v[42:45], v[10:11], off
	v_lshl_add_u64 v[10:11], v[10:11], 0, vcc
	v_readlane_b32 s0, v143, 8
	v_readlane_b32 s1, v143, 9
	v_readlane_b32 s16, v143, 10
	v_readlane_b32 s17, v143, 11
	s_waitcnt vmcnt(31)
	v_fmac_f32_e32 v8, s0, v46
	v_fmac_f32_e32 v9, s0, v47
	v_fmac_f32_e32 v6, s0, v48
	v_fmac_f32_e32 v7, s0, v49
	global_load_dwordx4 v[46:49], v[10:11], off offset:-4096
	s_waitcnt vmcnt(31)
	v_fmac_f32_e32 v8, s1, v50
	v_fmac_f32_e32 v9, s1, v51
	v_fmac_f32_e32 v6, s1, v52
	v_fmac_f32_e32 v7, s1, v53
	global_load_dwordx4 v[50:53], v[10:11], off
	v_lshl_add_u64 v[10:11], v[10:11], 0, vcc
	s_waitcnt vmcnt(31)
	v_fmac_f32_e32 v8, s16, v54
	v_fmac_f32_e32 v9, s16, v55
	v_fmac_f32_e32 v6, s16, v56
	v_fmac_f32_e32 v7, s16, v57
	global_load_dwordx4 v[54:57], v[10:11], off offset:-4096
	s_waitcnt vmcnt(31)
	v_fmac_f32_e32 v8, s17, v58
	v_fmac_f32_e32 v9, s17, v59
	v_fmac_f32_e32 v6, s17, v60
	v_fmac_f32_e32 v7, s17, v61
	global_load_dwordx4 v[58:61], v[10:11], off
	v_lshl_add_u64 v[10:11], v[10:11], 0, vcc
	v_readlane_b32 s0, v143, 12
	v_readlane_b32 s1, v143, 13
	v_readlane_b32 s16, v143, 14
	v_readlane_b32 s17, v143, 15
	s_waitcnt vmcnt(31)
	v_fmac_f32_e32 v8, s0, v62
	v_fmac_f32_e32 v9, s0, v63
	v_fmac_f32_e32 v6, s0, v64
	v_fmac_f32_e32 v7, s0, v65
	global_load_dwordx4 v[62:65], v[10:11], off offset:-4096
	s_waitcnt vmcnt(31)
	v_fmac_f32_e32 v8, s1, v66
	v_fmac_f32_e32 v9, s1, v67
	v_fmac_f32_e32 v6, s1, v68
	v_fmac_f32_e32 v7, s1, v69
	global_load_dwordx4 v[66:69], v[10:11], off
	v_lshl_add_u64 v[10:11], v[10:11], 0, vcc
	s_waitcnt vmcnt(31)
	v_fmac_f32_e32 v8, s16, v70
	v_fmac_f32_e32 v9, s16, v71
	v_fmac_f32_e32 v6, s16, v72
	v_fmac_f32_e32 v7, s16, v73
	global_load_dwordx4 v[70:73], v[10:11], off offset:-4096
	s_waitcnt vmcnt(31)
	v_fmac_f32_e32 v8, s17, v74
	v_fmac_f32_e32 v9, s17, v75
	v_fmac_f32_e32 v6, s17, v76
	v_fmac_f32_e32 v7, s17, v77
	global_load_dwordx4 v[74:77], v[10:11], off
	v_lshl_add_u64 v[10:11], v[10:11], 0, vcc
	v_readlane_b32 s0, v143, 16
	v_readlane_b32 s1, v143, 17
	v_readlane_b32 s16, v143, 18
	v_readlane_b32 s17, v143, 19
	s_waitcnt vmcnt(31)
	v_fmac_f32_e32 v8, s0, v78
	v_fmac_f32_e32 v9, s0, v79
	v_fmac_f32_e32 v6, s0, v80
	v_fmac_f32_e32 v7, s0, v81
	global_load_dwordx4 v[78:81], v[10:11], off offset:-4096
	s_waitcnt vmcnt(31)
	v_fmac_f32_e32 v8, s1, v82
	v_fmac_f32_e32 v9, s1, v83
	v_fmac_f32_e32 v6, s1, v84
	v_fmac_f32_e32 v7, s1, v85
	global_load_dwordx4 v[82:85], v[10:11], off
	v_lshl_add_u64 v[10:11], v[10:11], 0, vcc
	s_waitcnt vmcnt(31)
; DEVI void convert_layer(const Params& p, int layer, char* smem) {
;     ...
;         const float* pwr = pw + ((size_t)g * 128 + c) * 128;
;         const float* wor = wo + (size_t)(512 + g * 128) * 1024 + tid * 4;
;         f32x4 acc = f32x4{0.f, 0.f, 0.f, 0.f};
; #pragma unroll 8
;         for (int d = 0; d < 128; ++d) {
;           const float a = pwr[d] * ps[g * 128 + d];
;           const f32x4 w4 = *(const f32x4*)(wor + (size_t)d * 1024);
;           acc = acc + w4 * a;
;         }
	v_fmac_f32_e32 v8, s16, v86
	v_fmac_f32_e32 v9, s16, v87
	v_fmac_f32_e32 v6, s16, v88
	v_fmac_f32_e32 v7, s16, v89
	global_load_dwordx4 v[86:89], v[10:11], off offset:-4096
	s_waitcnt vmcnt(31)
	v_fmac_f32_e32 v8, s17, v90
	v_fmac_f32_e32 v9, s17, v91
	v_fmac_f32_e32 v6, s17, v92
	v_fmac_f32_e32 v7, s17, v93
	global_load_dwordx4 v[90:93], v[10:11], off
	v_lshl_add_u64 v[10:11], v[10:11], 0, vcc
	v_readlane_b32 s0, v143, 20
	v_readlane_b32 s1, v143, 21
	v_readlane_b32 s16, v143, 22
	v_readlane_b32 s17, v143, 23
	s_waitcnt vmcnt(31)
	v_fmac_f32_e32 v8, s0, v94
	v_fmac_f32_e32 v9, s0, v95
	v_fmac_f32_e32 v6, s0, v96
	v_fmac_f32_e32 v7, s0, v97
	global_load_dwordx4 v[94:97], v[10:11], off offset:-4096
	s_waitcnt vmcnt(31)
	v_fmac_f32_e32 v8, s1, v98
	v_fmac_f32_e32 v9, s1, v99
	v_fmac_f32_e32 v6, s1, v100
	v_fmac_f32_e32 v7, s1, v101
	global_load_dwordx4 v[98:101], v[10:11], off
	v_lshl_add_u64 v[10:11], v[10:11], 0, vcc
	s_waitcnt vmcnt(31)
	v_fmac_f32_e32 v8, s16, v102
	v_fmac_f32_e32 v9, s16, v103
	v_fmac_f32_e32 v6, s16, v104
	v_fmac_f32_e32 v7, s16, v105
	global_load_dwordx4 v[102:105], v[10:11], off offset:-4096
	s_waitcnt vmcnt(31)
	v_fmac_f32_e32 v8, s17, v106
	v_fmac_f32_e32 v9, s17, v107
	v_fmac_f32_e32 v6, s17, v108
	v_fmac_f32_e32 v7, s17, v109
	global_load_dwordx4 v[106:109], v[10:11], off
	v_lshl_add_u64 v[10:11], v[10:11], 0, vcc
	v_readlane_b32 s0, v143, 24
	v_readlane_b32 s1, v143, 25
	v_readlane_b32 s16, v143, 26
	v_readlane_b32 s17, v143, 27
	s_waitcnt vmcnt(31)
	v_fmac_f32_e32 v8, s0, v110
	v_fmac_f32_e32 v9, s0, v111
	v_fmac_f32_e32 v6, s0, v112
	v_fmac_f32_e32 v7, s0, v113
	global_load_dwordx4 v[110:113], v[10:11], off offset:-4096
	s_waitcnt vmcnt(31)
	v_fmac_f32_e32 v8, s1, v114
	v_fmac_f32_e32 v9, s1, v115
	v_fmac_f32_e32 v6, s1, v116
	v_fmac_f32_e32 v7, s1, v117
	global_load_dwordx4 v[114:117], v[10:11], off
	v_lshl_add_u64 v[10:11], v[10:11], 0, vcc
	s_waitcnt vmcnt(31)
	v_fmac_f32_e32 v8, s16, v118
	v_fmac_f32_e32 v9, s16, v119
	v_fmac_f32_e32 v6, s16, v120
	v_fmac_f32_e32 v7, s16, v121
	global_load_dwordx4 v[118:121], v[10:11], off offset:-4096
	s_waitcnt vmcnt(31)
	v_fmac_f32_e32 v8, s17, v122
	v_fmac_f32_e32 v9, s17, v123
	v_fmac_f32_e32 v6, s17, v124
	v_fmac_f32_e32 v7, s17, v125
	global_load_dwordx4 v[122:125], v[10:11], off
	v_lshl_add_u64 v[10:11], v[10:11], 0, vcc
	v_readlane_b32 s0, v143, 28
	v_readlane_b32 s1, v143, 29
	v_readlane_b32 s16, v143, 30
	v_readlane_b32 s17, v143, 31
	s_waitcnt vmcnt(31)
	v_fmac_f32_e32 v8, s0, v126
	v_fmac_f32_e32 v9, s0, v127
	v_fmac_f32_e32 v6, s0, v128
	v_fmac_f32_e32 v7, s0, v129
	global_load_dwordx4 v[126:129], v[10:11], off offset:-4096
	s_waitcnt vmcnt(31)
	v_fmac_f32_e32 v8, s1, v130
	v_fmac_f32_e32 v9, s1, v131
	v_fmac_f32_e32 v6, s1, v132
	v_fmac_f32_e32 v7, s1, v133
	global_load_dwordx4 v[130:133], v[10:11], off
	v_lshl_add_u64 v[10:11], v[10:11], 0, vcc
	s_waitcnt vmcnt(31)
	v_fmac_f32_e32 v8, s16, v134
	v_fmac_f32_e32 v9, s16, v135
	v_fmac_f32_e32 v6, s16, v136
	v_fmac_f32_e32 v7, s16, v137
	global_load_dwordx4 v[134:137], v[10:11], off offset:-4096
	s_waitcnt vmcnt(31)
	v_fmac_f32_e32 v8, s17, v138
	v_fmac_f32_e32 v9, s17, v139
	v_fmac_f32_e32 v6, s17, v140
	v_fmac_f32_e32 v7, s17, v141
	global_load_dwordx4 v[138:141], v[10:11], off
	v_lshl_add_u64 v[10:11], v[10:11], 0, vcc
	v_readlane_b32 s0, v143, 32
	v_readlane_b32 s1, v143, 33
	v_readlane_b32 s16, v143, 34
	v_readlane_b32 s17, v143, 35
	s_waitcnt vmcnt(31)
	v_fmac_f32_e32 v8, s0, v14
	v_fmac_f32_e32 v9, s0, v15
	v_fmac_f32_e32 v6, s0, v16
	v_fmac_f32_e32 v7, s0, v17
	s_waitcnt vmcnt(30)
	v_fmac_f32_e32 v8, s1, v18
	v_fmac_f32_e32 v9, s1, v19
	v_fmac_f32_e32 v6, s1, v20
	v_fmac_f32_e32 v7, s1, v21
	s_waitcnt vmcnt(29)
	v_fmac_f32_e32 v8, s16, v22
	v_fmac_f32_e32 v9, s16, v23
	v_fmac_f32_e32 v6, s16, v24
	v_fmac_f32_e32 v7, s16, v25
	s_waitcnt vmcnt(28)
	v_fmac_f32_e32 v8, s17, v26
	v_fmac_f32_e32 v9, s17, v27
	v_fmac_f32_e32 v6, s17, v28
	v_fmac_f32_e32 v7, s17, v29
	v_readlane_b32 s0, v143, 36
	v_readlane_b32 s1, v143, 37
	v_readlane_b32 s16, v143, 38
	v_readlane_b32 s17, v143, 39
	s_waitcnt vmcnt(27)
	v_fmac_f32_e32 v8, s0, v30
	v_fmac_f32_e32 v9, s0, v31
	v_fmac_f32_e32 v6, s0, v32
	v_fmac_f32_e32 v7, s0, v33
	s_waitcnt vmcnt(26)
	v_fmac_f32_e32 v8, s1, v34
	v_fmac_f32_e32 v9, s1, v35
	v_fmac_f32_e32 v6, s1, v36
	v_fmac_f32_e32 v7, s1, v37
	s_waitcnt vmcnt(25)
	v_fmac_f32_e32 v8, s16, v38
	v_fmac_f32_e32 v9, s16, v39
	v_fmac_f32_e32 v6, s16, v40
	v_fmac_f32_e32 v7, s16, v41
	s_waitcnt vmcnt(24)
	v_fmac_f32_e32 v8, s17, v42
	v_fmac_f32_e32 v9, s17, v43
	v_fmac_f32_e32 v6, s17, v44
	v_fmac_f32_e32 v7, s17, v45
	v_readlane_b32 s0, v143, 40
	v_readlane_b32 s1, v143, 41
	v_readlane_b32 s16, v143, 42
	v_readlane_b32 s17, v143, 43
	s_waitcnt vmcnt(23)
; DEVI bf16_t f2bf(float a) { return (bf16_t)(pack2(a, 0.f) & 0xffff); }
; DEVI void convert_layer(const Params& p, int layer, char* smem) {
;     ...
;         for (int d = 0; d < 128; ++d) {
;           const float a = pwr[d] * ps[g * 128 + d];
;           const f32x4 w4 = *(const f32x4*)(wor + (size_t)d * 1024);
;           acc = acc + w4 * a;
;         }
; #pragma unroll
;         for (int e = 0; e < 4; ++e) wb[WB_OUT + wfm(tid * 4 + e, 512 + item, 1024)] = f2bf(acc[e]);
;       }
	v_fmac_f32_e32 v8, s0, v46
	v_fmac_f32_e32 v9, s0, v47
	v_fmac_f32_e32 v6, s0, v48
	v_fmac_f32_e32 v7, s0, v49
	s_waitcnt vmcnt(22)
	v_fmac_f32_e32 v8, s1, v50
	v_fmac_f32_e32 v9, s1, v51
	v_fmac_f32_e32 v6, s1, v52
	v_fmac_f32_e32 v7, s1, v53
	s_waitcnt vmcnt(21)
	v_fmac_f32_e32 v8, s16, v54
	v_fmac_f32_e32 v9, s16, v55
	v_fmac_f32_e32 v6, s16, v56
	v_fmac_f32_e32 v7, s16, v57
	s_waitcnt vmcnt(20)
	v_fmac_f32_e32 v8, s17, v58
	v_fmac_f32_e32 v9, s17, v59
	v_fmac_f32_e32 v6, s17, v60
	v_fmac_f32_e32 v7, s17, v61
	v_readlane_b32 s0, v143, 44
	v_readlane_b32 s1, v143, 45
	v_readlane_b32 s16, v143, 46
	v_readlane_b32 s17, v143, 47
	s_waitcnt vmcnt(19)
	v_fmac_f32_e32 v8, s0, v62
	v_fmac_f32_e32 v9, s0, v63
	v_fmac_f32_e32 v6, s0, v64
	v_fmac_f32_e32 v7, s0, v65
	s_waitcnt vmcnt(18)
	v_fmac_f32_e32 v8, s1, v66
	v_fmac_f32_e32 v9, s1, v67
	v_fmac_f32_e32 v6, s1, v68
	v_fmac_f32_e32 v7, s1, v69
	s_waitcnt vmcnt(17)
	v_fmac_f32_e32 v8, s16, v70
	v_fmac_f32_e32 v9, s16, v71
	v_fmac_f32_e32 v6, s16, v72
	v_fmac_f32_e32 v7, s16, v73
	s_waitcnt vmcnt(16)
	v_fmac_f32_e32 v8, s17, v74
	v_fmac_f32_e32 v9, s17, v75
	v_fmac_f32_e32 v6, s17, v76
	v_fmac_f32_e32 v7, s17, v77
	v_readlane_b32 s0, v143, 48
	v_readlane_b32 s1, v143, 49
	v_readlane_b32 s16, v143, 50
	v_readlane_b32 s17, v143, 51
	s_waitcnt vmcnt(15)
	v_fmac_f32_e32 v8, s0, v78
	v_fmac_f32_e32 v9, s0, v79
	v_fmac_f32_e32 v6, s0, v80
	v_fmac_f32_e32 v7, s0, v81
	s_waitcnt vmcnt(14)
	v_fmac_f32_e32 v8, s1, v82
	v_fmac_f32_e32 v9, s1, v83
	v_fmac_f32_e32 v6, s1, v84
	v_fmac_f32_e32 v7, s1, v85
	s_waitcnt vmcnt(13)
	v_fmac_f32_e32 v8, s16, v86
	v_fmac_f32_e32 v9, s16, v87
	v_fmac_f32_e32 v6, s16, v88
	v_fmac_f32_e32 v7, s16, v89
	s_waitcnt vmcnt(12)
	v_fmac_f32_e32 v8, s17, v90
	v_fmac_f32_e32 v9, s17, v91
	v_fmac_f32_e32 v6, s17, v92
	v_fmac_f32_e32 v7, s17, v93
	v_readlane_b32 s0, v143, 52
	v_readlane_b32 s1, v143, 53
	v_readlane_b32 s16, v143, 54
	v_readlane_b32 s17, v143, 55
	s_waitcnt vmcnt(11)
	v_fmac_f32_e32 v8, s0, v94
	v_fmac_f32_e32 v9, s0, v95
	v_fmac_f32_e32 v6, s0, v96
	v_fmac_f32_e32 v7, s0, v97
	s_waitcnt vmcnt(10)
	v_fmac_f32_e32 v8, s1, v98
	v_fmac_f32_e32 v9, s1, v99
	v_fmac_f32_e32 v6, s1, v100
	v_fmac_f32_e32 v7, s1, v101
	s_waitcnt vmcnt(9)
	v_fmac_f32_e32 v8, s16, v102
	v_fmac_f32_e32 v9, s16, v103
	v_fmac_f32_e32 v6, s16, v104
	v_fmac_f32_e32 v7, s16, v105
	s_waitcnt vmcnt(8)
	v_fmac_f32_e32 v8, s17, v106
	v_fmac_f32_e32 v9, s17, v107
	v_fmac_f32_e32 v6, s17, v108
	v_fmac_f32_e32 v7, s17, v109
	v_readlane_b32 s0, v143, 56
	v_readlane_b32 s1, v143, 57
	v_readlane_b32 s16, v143, 58
	v_readlane_b32 s17, v143, 59
	s_waitcnt vmcnt(7)
	v_fmac_f32_e32 v8, s0, v110
	v_fmac_f32_e32 v9, s0, v111
	v_fmac_f32_e32 v6, s0, v112
	v_fmac_f32_e32 v7, s0, v113
	s_waitcnt vmcnt(6)
	v_fmac_f32_e32 v8, s1, v114
	v_fmac_f32_e32 v9, s1, v115
	v_fmac_f32_e32 v6, s1, v116
	v_fmac_f32_e32 v7, s1, v117
	s_waitcnt vmcnt(5)
	v_fmac_f32_e32 v8, s16, v118
	v_fmac_f32_e32 v9, s16, v119
	v_fmac_f32_e32 v6, s16, v120
	v_fmac_f32_e32 v7, s16, v121
	s_waitcnt vmcnt(4)
	v_fmac_f32_e32 v8, s17, v122
	v_fmac_f32_e32 v9, s17, v123
	v_fmac_f32_e32 v6, s17, v124
	v_fmac_f32_e32 v7, s17, v125
	v_readlane_b32 s0, v143, 60
	v_readlane_b32 s1, v143, 61
	v_readlane_b32 s16, v143, 62
	v_readlane_b32 s17, v143, 63
	s_waitcnt vmcnt(3)
	v_fmac_f32_e32 v8, s0, v126
	v_fmac_f32_e32 v9, s0, v127
	v_fmac_f32_e32 v6, s0, v128
	v_fmac_f32_e32 v7, s0, v129
	s_waitcnt vmcnt(2)
	v_fmac_f32_e32 v8, s1, v130
	v_fmac_f32_e32 v9, s1, v131
	v_fmac_f32_e32 v6, s1, v132
	v_fmac_f32_e32 v7, s1, v133
	s_waitcnt vmcnt(1)
	v_fmac_f32_e32 v8, s16, v134
	v_fmac_f32_e32 v9, s16, v135
	v_fmac_f32_e32 v6, s16, v136
	v_fmac_f32_e32 v7, s16, v137
	s_waitcnt vmcnt(0)
	v_fmac_f32_e32 v8, s17, v138
	v_fmac_f32_e32 v9, s17, v139
	v_fmac_f32_e32 v6, s17, v140
	v_fmac_f32_e32 v7, s17, v141
	s_add_i32 s0, s5, 0x200
	s_ashr_i32 s0, s0, 5
	s_ashr_i32 s1, s0, 31
	s_lshl_b32 s7, s5, 1
	v_and_or_b32 v0, s7, 48, v12
	s_and_b32 s7, s5, 7
	s_lshl_b64 s[0:1], s[0:1], 10
	v_lshl_add_u64 v[10:11], v[2:3], 0, s[0:1]
	s_lshl_b32 s62, s7, 1
	v_lshl_add_u64 v[10:11], v[10:11], 0, s[62:63]
	v_lshlrev_b32_e32 v0, 4, v0
	v_cvt_pk_bf16_f32 v8, v8, s0
	v_lshl_add_u64 v[10:11], v[10:11], 0, v[0:1]
	s_mov_b32 s0, 0x840000
	v_add_co_u32_e32 v10, vcc, s0, v10
	v_cvt_pk_bf16_f32 v0, v9, s0
	s_nop 0
	v_addc_co_u32_e32 v11, vcc, 0, v11, vcc
	global_store_short v[10:11], v0, off offset:16
	v_cvt_pk_bf16_f32 v0, v6, s0
	global_store_short v[10:11], v0, off offset:32
	v_cvt_pk_bf16_f32 v0, v7, s0
	v_readlane_b32 s0, v248, 48
	s_add_i32 s5, s5, s48
	s_add_i32 s6, s6, s0
	s_cmpk_gt_i32 s5, 0x1ff
	global_store_short v[10:11], v8, off
	global_store_short v[10:11], v0, off offset:48
	s_cbranch_scc0 .LBB0_1976
